# out-proj hyena K tiles: loader re-mapped (lane=channel) so the transposing 16-bit LDS stores are bank-conflict-free; RMW epilogues of phases 8/11 keep all 64 loads in flight
# speedup vs baseline: 1.0262x; 1.0262x over previous
; DI int crow(int reg, int h) { return (reg & 3) + 8 * (reg >> 2) + 4 * h; }
; #define XCD_TILE_LOOP(MT, NTN, m_, n_) for (int lt_ = (bid >> 3), m_ = 0, n_ = 0; (lt_ < ((MT) >> 3) * (NTN)) && ((m_ = (bid & 7) + 8 * (lt_ / (NTN))), (n_ = lt_ % (NTN)), true); lt_ += (G >> 3))
; template <class Epi, class ColV>
; DI void gemm_tile(const bf16_t* __restrict__ A, int lda, const bf16_t* __restrict__ Bt, int ldb, int K, int m0, int n0, unsigned char* smem, Epi epi, ColV colv, const bf16_t* __restrict__ HYT = nullptr) {
;     ...
;     const float cv0 = colv(m0, n0 + 64 * wc + li), cv1 = colv(m0, n0 + 64 * wc + 32 + li);
; #pragma unroll
;     for (int mi = 0; mi < 2; ++mi)
; #pragma unroll
;         for (int ni = 0; ni < 2; ++ni)
; #pragma unroll
;             for (int reg = 0; reg < 16; ++reg)
;                 epi(m0 + 64 * wr + 32 * mi + crow(reg, lh), n0 + 64 * wc + 32 * ni + li, acc[mi][ni][reg], ni ? cv1 : cv0);
;     ...
;         auto epi = [&](int r, int c, float v, float ga) {
;             if (r < NL) out[(size_t)r * 1024 + c] += ga * v;
;             else XC[(size_t)(r - NL) * 1024 + c] += ga * v; };
;         XCD_TILE_LOOP(NL / 128, 8, tm, tn) gemm_tile((const bf16_t*)(p.ws + WS_HID), 4096, (const bf16_t*)(p.ws + wbase(layer) + W_FF2), 4096, 4096, tm * 128, tn * 128, smem, epi, gate);
.LBB0_37:
	s_ashr_i32 s12, s39, 12
	s_mulk_i32 s12, 0x1800
	s_add_i32 s13, s12, 0x1400
	v_or_b32_e32 v68, s40, v166
	v_or_b32_e32 v0, s13, v148
	v_add_u32_e32 v0, v0, v68
	v_readlane_b32 s18, v255, 30
	v_ashrrev_i32_e32 v1, 31, v0
	v_readlane_b32 s19, v255, 31
	s_addk_i32 s12, 0x1420
	v_mov_b32_e32 v82, s97
	v_lshl_add_u64 v[0:1], v[0:1], 2, s[18:19]
	global_load_dword v80, v[0:1], off
	v_or_b32_e32 v0, s12, v148
	v_add_u32_e32 v0, v0, v68
	v_ashrrev_i32_e32 v1, 31, v0
	v_lshl_add_u64 v[0:1], v[0:1], 2, s[18:19]
	global_load_dword v2, v[0:1], off
	v_add_u32_e32 v0, s38, v167
	v_lshl_or_b32 v81, v151, 2, v0
	v_or_b32_e32 v0, v68, v148
	v_lshlrev_b32_e32 v81, 12, v81
	v_lshl_add_u32 v81, v0, 2, v81
	v_mov_b32_e32 v0, v81
	global_load_dword v84, v0, s[24:25]
	global_load_dword v85, v0, s[24:25] offset:128
	v_add_u32_e32 v0, 0x1000, v0
	global_load_dword v86, v0, s[24:25]
	global_load_dword v87, v0, s[24:25] offset:128
	v_add_u32_e32 v0, 0x1000, v0
	global_load_dword v88, v0, s[24:25]
	global_load_dword v89, v0, s[24:25] offset:128
	v_add_u32_e32 v0, 0x1000, v0
	global_load_dword v90, v0, s[24:25]
	global_load_dword v91, v0, s[24:25] offset:128
	v_add_u32_e32 v0, 0x5000, v0
	global_load_dword v92, v0, s[24:25]
	global_load_dword v93, v0, s[24:25] offset:128
	v_add_u32_e32 v0, 0x1000, v0
	global_load_dword v94, v0, s[24:25]
	global_load_dword v95, v0, s[24:25] offset:128
	v_add_u32_e32 v0, 0x1000, v0
	global_load_dword v96, v0, s[24:25]
	global_load_dword v97, v0, s[24:25] offset:128
	v_add_u32_e32 v0, 0x1000, v0
	global_load_dword v98, v0, s[24:25]
	global_load_dword v99, v0, s[24:25] offset:128
	v_add_u32_e32 v0, 0x5000, v0
	global_load_dword v100, v0, s[24:25]
	global_load_dword v101, v0, s[24:25] offset:128
	v_add_u32_e32 v0, 0x1000, v0
	global_load_dword v102, v0, s[24:25]
	global_load_dword v103, v0, s[24:25] offset:128
	v_add_u32_e32 v0, 0x1000, v0
	global_load_dword v104, v0, s[24:25]
	global_load_dword v105, v0, s[24:25] offset:128
	v_add_u32_e32 v0, 0x1000, v0
	global_load_dword v106, v0, s[24:25]
	global_load_dword v107, v0, s[24:25] offset:128
	v_add_u32_e32 v0, 0x5000, v0
	global_load_dword v108, v0, s[24:25]
	global_load_dword v109, v0, s[24:25] offset:128
	v_add_u32_e32 v0, 0x1000, v0
	global_load_dword v110, v0, s[24:25]
	global_load_dword v111, v0, s[24:25] offset:128
	v_add_u32_e32 v0, 0x1000, v0
	global_load_dword v112, v0, s[24:25]
	global_load_dword v113, v0, s[24:25] offset:128
	v_add_u32_e32 v0, 0x1000, v0
	global_load_dword v114, v0, s[24:25]
	global_load_dword v115, v0, s[24:25] offset:128
	v_add_u32_e32 v0, 0x20000, v81
	global_load_dword v116, v0, s[24:25]
	global_load_dword v117, v0, s[24:25] offset:128
	v_add_u32_e32 v0, 0x1000, v0
	global_load_dword v118, v0, s[24:25]
	global_load_dword v119, v0, s[24:25] offset:128
	v_add_u32_e32 v0, 0x1000, v0
	global_load_dword v120, v0, s[24:25]
	global_load_dword v121, v0, s[24:25] offset:128
	v_add_u32_e32 v0, 0x1000, v0
	global_load_dword v122, v0, s[24:25]
	global_load_dword v123, v0, s[24:25] offset:128
	v_add_u32_e32 v0, 0x5000, v0
	global_load_dword v124, v0, s[24:25]
	global_load_dword v125, v0, s[24:25] offset:128
	v_add_u32_e32 v0, 0x1000, v0
	global_load_dword v126, v0, s[24:25]
	global_load_dword v127, v0, s[24:25] offset:128
	v_add_u32_e32 v0, 0x1000, v0
	global_load_dword v128, v0, s[24:25]
	global_load_dword v129, v0, s[24:25] offset:128
	v_add_u32_e32 v0, 0x1000, v0
	global_load_dword v130, v0, s[24:25]
	global_load_dword v131, v0, s[24:25] offset:128
	v_add_u32_e32 v0, 0x5000, v0
	global_load_dword v132, v0, s[24:25]
	global_load_dword v133, v0, s[24:25] offset:128
	v_add_u32_e32 v0, 0x1000, v0
	global_load_dword v134, v0, s[24:25]
	global_load_dword v135, v0, s[24:25] offset:128
	v_add_u32_e32 v0, 0x1000, v0
	global_load_dword v136, v0, s[24:25]
	global_load_dword v137, v0, s[24:25] offset:128
	v_add_u32_e32 v0, 0x1000, v0
	global_load_dword v138, v0, s[24:25]
	global_load_dword v139, v0, s[24:25] offset:128
	v_add_u32_e32 v0, 0x5000, v0
	global_load_dword v140, v0, s[24:25]
	global_load_dword v141, v0, s[24:25] offset:128
	v_add_u32_e32 v0, 0x1000, v0
	global_load_dword v142, v0, s[24:25]
	global_load_dword v143, v0, s[24:25] offset:128
	v_add_u32_e32 v0, 0x1000, v0
	global_load_dword v144, v0, s[24:25]
	global_load_dword v145, v0, s[24:25] offset:128
	v_add_u32_e32 v0, 0x1000, v0
	global_load_dword v146, v0, s[24:25]
	global_load_dword v147, v0, s[24:25] offset:128
	s_waitcnt vmcnt(32)
; #define XCD_TILE_LOOP(MT, NTN, m_, n_) for (int lt_ = (bid >> 3), m_ = 0, n_ = 0; (lt_ < ((MT) >> 3) * (NTN)) && ((m_ = (bid & 7) + 8 * (lt_ / (NTN))), (n_ = lt_ % (NTN)), true); lt_ += (G >> 3))
;     ...
;         auto epi = [&](int r, int c, float v, float ga) {
;             if (r < NL) out[(size_t)r * 1024 + c] += ga * v;
;             else XC[(size_t)(r - NL) * 1024 + c] += ga * v; };
;         XCD_TILE_LOOP(NL / 128, 8, tm, tn) gemm_tile((const bf16_t*)(p.ws + WS_HID), 4096, (const bf16_t*)(p.ws + wbase(layer) + W_FF2), 4096, 4096, tm * 128, tn * 128, smem, epi, gate);
	v_fmac_f32_e32 v84, v52, v80
	v_fmac_f32_e32 v85, v36, v2
	v_fmac_f32_e32 v86, v53, v80
	v_fmac_f32_e32 v87, v37, v2
	v_fmac_f32_e32 v88, v54, v80
	v_fmac_f32_e32 v89, v38, v2
	v_fmac_f32_e32 v90, v55, v80
	v_fmac_f32_e32 v91, v39, v2
	v_fmac_f32_e32 v92, v56, v80
	v_fmac_f32_e32 v93, v40, v2
	v_fmac_f32_e32 v94, v57, v80
	v_fmac_f32_e32 v95, v41, v2
	v_fmac_f32_e32 v96, v58, v80
	v_fmac_f32_e32 v97, v42, v2
	v_fmac_f32_e32 v98, v59, v80
	v_fmac_f32_e32 v99, v43, v2
	v_fmac_f32_e32 v100, v60, v80
	v_fmac_f32_e32 v101, v44, v2
	v_fmac_f32_e32 v102, v61, v80
	v_fmac_f32_e32 v103, v45, v2
	v_fmac_f32_e32 v104, v62, v80
	v_fmac_f32_e32 v105, v46, v2
	v_fmac_f32_e32 v106, v63, v80
	v_fmac_f32_e32 v107, v47, v2
	v_fmac_f32_e32 v108, v64, v80
	v_fmac_f32_e32 v109, v48, v2
	v_fmac_f32_e32 v110, v65, v80
	v_fmac_f32_e32 v111, v49, v2
	v_fmac_f32_e32 v112, v66, v80
	v_fmac_f32_e32 v113, v50, v2
	v_fmac_f32_e32 v114, v67, v80
	v_fmac_f32_e32 v115, v51, v2
	v_mov_b32_e32 v0, v81
	global_store_dword v0, v84, s[24:25]
	global_store_dword v0, v85, s[24:25] offset:128
	v_add_u32_e32 v0, 0x1000, v0
	global_store_dword v0, v86, s[24:25]
	global_store_dword v0, v87, s[24:25] offset:128
	v_add_u32_e32 v0, 0x1000, v0
	global_store_dword v0, v88, s[24:25]
	global_store_dword v0, v89, s[24:25] offset:128
	v_add_u32_e32 v0, 0x1000, v0
	global_store_dword v0, v90, s[24:25]
	global_store_dword v0, v91, s[24:25] offset:128
	v_add_u32_e32 v0, 0x5000, v0
	global_store_dword v0, v92, s[24:25]
	global_store_dword v0, v93, s[24:25] offset:128
	v_add_u32_e32 v0, 0x1000, v0
	global_store_dword v0, v94, s[24:25]
	global_store_dword v0, v95, s[24:25] offset:128
	v_add_u32_e32 v0, 0x1000, v0
	global_store_dword v0, v96, s[24:25]
	global_store_dword v0, v97, s[24:25] offset:128
	v_add_u32_e32 v0, 0x1000, v0
	global_store_dword v0, v98, s[24:25]
	global_store_dword v0, v99, s[24:25] offset:128
	v_add_u32_e32 v0, 0x5000, v0
	global_store_dword v0, v100, s[24:25]
	global_store_dword v0, v101, s[24:25] offset:128
	v_add_u32_e32 v0, 0x1000, v0
	global_store_dword v0, v102, s[24:25]
	global_store_dword v0, v103, s[24:25] offset:128
	v_add_u32_e32 v0, 0x1000, v0
	global_store_dword v0, v104, s[24:25]
	global_store_dword v0, v105, s[24:25] offset:128
	v_add_u32_e32 v0, 0x1000, v0
	global_store_dword v0, v106, s[24:25]
	global_store_dword v0, v107, s[24:25] offset:128
	v_add_u32_e32 v0, 0x5000, v0
	global_store_dword v0, v108, s[24:25]
	global_store_dword v0, v109, s[24:25] offset:128
	v_add_u32_e32 v0, 0x1000, v0
	global_store_dword v0, v110, s[24:25]
	global_store_dword v0, v111, s[24:25] offset:128
	v_add_u32_e32 v0, 0x1000, v0
	global_store_dword v0, v112, s[24:25]
	global_store_dword v0, v113, s[24:25] offset:128
	v_add_u32_e32 v0, 0x1000, v0
	global_store_dword v0, v114, s[24:25]
	global_store_dword v0, v115, s[24:25] offset:128
	s_waitcnt vmcnt(32)
	v_fmac_f32_e32 v116, v20, v80
	v_fmac_f32_e32 v117, v4, v2
	v_fmac_f32_e32 v118, v21, v80
	v_fmac_f32_e32 v119, v5, v2
	v_fmac_f32_e32 v120, v22, v80
	v_fmac_f32_e32 v121, v6, v2
	v_fmac_f32_e32 v122, v23, v80
	v_fmac_f32_e32 v123, v7, v2
	v_fmac_f32_e32 v124, v24, v80
	v_fmac_f32_e32 v125, v8, v2
	v_fmac_f32_e32 v126, v25, v80
	v_fmac_f32_e32 v127, v9, v2
	v_fmac_f32_e32 v128, v26, v80
	v_fmac_f32_e32 v129, v10, v2
	v_fmac_f32_e32 v130, v27, v80
	v_fmac_f32_e32 v131, v11, v2
	v_fmac_f32_e32 v132, v28, v80
	v_fmac_f32_e32 v133, v12, v2
	v_fmac_f32_e32 v134, v29, v80
	v_fmac_f32_e32 v135, v13, v2
	v_fmac_f32_e32 v136, v30, v80
	v_fmac_f32_e32 v137, v14, v2
	v_fmac_f32_e32 v138, v31, v80
	v_fmac_f32_e32 v139, v15, v2
	v_fmac_f32_e32 v140, v32, v80
	v_fmac_f32_e32 v141, v16, v2
	v_fmac_f32_e32 v142, v33, v80
	v_fmac_f32_e32 v143, v17, v2
	v_fmac_f32_e32 v144, v34, v80
	v_fmac_f32_e32 v145, v18, v2
	v_fmac_f32_e32 v146, v35, v80
	v_fmac_f32_e32 v147, v19, v2
	v_add_u32_e32 v0, 0x20000, v81
	global_store_dword v0, v116, s[24:25]
	global_store_dword v0, v117, s[24:25] offset:128
	v_add_u32_e32 v0, 0x1000, v0
	global_store_dword v0, v118, s[24:25]
	global_store_dword v0, v119, s[24:25] offset:128
	v_add_u32_e32 v0, 0x1000, v0
	global_store_dword v0, v120, s[24:25]
	global_store_dword v0, v121, s[24:25] offset:128
	v_add_u32_e32 v0, 0x1000, v0
	global_store_dword v0, v122, s[24:25]
	global_store_dword v0, v123, s[24:25] offset:128
	v_add_u32_e32 v0, 0x5000, v0
	global_store_dword v0, v124, s[24:25]
	global_store_dword v0, v125, s[24:25] offset:128
	v_add_u32_e32 v0, 0x1000, v0
	global_store_dword v0, v126, s[24:25]
	global_store_dword v0, v127, s[24:25] offset:128
	v_add_u32_e32 v0, 0x1000, v0
	global_store_dword v0, v128, s[24:25]
	global_store_dword v0, v129, s[24:25] offset:128
	v_add_u32_e32 v0, 0x1000, v0
	global_store_dword v0, v130, s[24:25]
	global_store_dword v0, v131, s[24:25] offset:128
	v_add_u32_e32 v0, 0x5000, v0
	global_store_dword v0, v132, s[24:25]
	global_store_dword v0, v133, s[24:25] offset:128
	v_add_u32_e32 v0, 0x1000, v0
	global_store_dword v0, v134, s[24:25]
	global_store_dword v0, v135, s[24:25] offset:128
	v_add_u32_e32 v0, 0x1000, v0
	global_store_dword v0, v136, s[24:25]
	global_store_dword v0, v137, s[24:25] offset:128
	v_add_u32_e32 v0, 0x1000, v0
	global_store_dword v0, v138, s[24:25]
	global_store_dword v0, v139, s[24:25] offset:128
	v_add_u32_e32 v0, 0x5000, v0
	global_store_dword v0, v140, s[24:25]
	global_store_dword v0, v141, s[24:25] offset:128
	v_add_u32_e32 v0, 0x1000, v0
	global_store_dword v0, v142, s[24:25]
	global_store_dword v0, v143, s[24:25] offset:128
	v_add_u32_e32 v0, 0x1000, v0
	global_store_dword v0, v144, s[24:25]
	global_store_dword v0, v145, s[24:25] offset:128
	v_add_u32_e32 v0, 0x1000, v0
	global_store_dword v0, v146, s[24:25]
	global_store_dword v0, v147, s[24:25] offset:128
	s_add_i32 s37, s37, s36
	s_cmpk_lt_i32 s37, 0x80
	s_cbranch_scc0 .LBB0_46

; template <class Epi, class ColV>
; DI void gemm_tile(const bf16_t* __restrict__ A, int lda, const bf16_t* __restrict__ Bt, int ldb, int K, int m0, int n0, unsigned char* smem, Epi epi, ColV colv, const bf16_t* __restrict__ HYT = nullptr) {
;     ...
;     auto gload = [&](u32x4 (&r)[8], int kt) {
; #pragma unroll
;         for (int i = 0; i < 4; ++i) { int id = tid + 256 * i, row = id >> 3, kc = id & 7;
;             if (HYT && kt >= 12) r[i] = *(const u32x4*)(HYT + (size_t)((kt - 12) * 64 + (id >> 4)) * NT + m0 + (id & 15) * 8);
;             else r[i] = *(const u32x4*)(A + (size_t)(m0 + row) * lda + kt * 64 + kc * 8);
;             r[4 + i] = *(const u32x4*)(Bt + (size_t)(n0 + row) * ldb + kt * 64 + kc * 8); }
;     };
;     auto sstore = [&](const u32x4 (&r)[8], int buf, int kt) {
; #pragma unroll
;         for (int i = 0; i < 4; ++i) { int id = tid + 256 * i, row = id >> 3, kc = id & 7;
;             if (HYT && kt >= 12) { const int kk = id >> 4, rr = (id & 15) * 8; bf16_t* d = As + (buf * 128 + rr) * LS + kk; const bf16x8 v = __builtin_bit_cast(bf16x8, r[i]);
; #pragma unroll
;                 for (int e = 0; e < 8; ++e) d[e * LS] = (bf16_t)v[e]; }
;             else *(u32x4*)(As + (buf * 128 + row) * LS + kc * 8) = r[i];
;             *(u32x4*)(Bs + (buf * 128 + row) * LS + kc * 8) = r[4 + i]; }
;     };
;     ...
;     gload(R0, 0); gload(R1, 1);
;     sstore(R0, 0, 0); __syncthreads();
.LBB0_79:
	s_ashr_i32 s12, s37, 31
	s_lshr_b32 s12, s12, 29
	s_add_i32 s12, s37, s12
	s_lshl_b32 s12, s12, 7
	s_and_b32 s38, s12, 0xfffffc00
	v_mov_b32_e32 v151, v168
	s_or_b32 s12, s38, s76
	s_ashr_i32 s13, s12, 31
	v_ashrrev_i32_e32 v38, 3, v151
	v_add_u32_e32 v0, s12, v38
	v_ashrrev_i32_e32 v1, 31, v0
	v_lshlrev_b64 v[0:1], 11, v[0:1]
	v_lshlrev_b32_e32 v2, 4, v151
	v_add_u32_e32 v40, 0x100, v151
	v_lshl_add_u64 v[0:1], s[94:95], 0, v[0:1]
	v_and_b32_e32 v2, 0x70, v2
	v_ashrrev_i32_e32 v41, 3, v40
	v_lshl_add_u64 v[160:161], v[0:1], 0, v[2:3]
	v_subrev_u32_e32 v0, s38, v38
	v_subrev_u32_e32 v16, s38, v41
	v_add_u32_e32 v42, 0x200, v151
	v_add_u32_e32 v0, s36, v0
	v_add_u32_e32 v12, s12, v41
	v_add_u32_e32 v16, s36, v16
	v_ashrrev_i32_e32 v43, 3, v42
	v_ashrrev_i32_e32 v1, 31, v0
	v_ashrrev_i32_e32 v13, 31, v12
	v_ashrrev_i32_e32 v17, 31, v16
	v_subrev_u32_e32 v24, s38, v43
	v_add_u32_e32 v44, 0x300, v151
	v_lshlrev_b64 v[0:1], 11, v[0:1]
	v_lshlrev_b64 v[12:13], 11, v[12:13]
	v_lshlrev_b64 v[16:17], 11, v[16:17]
	v_add_u32_e32 v20, s12, v43
	v_add_u32_e32 v24, s36, v24
	v_ashrrev_i32_e32 v45, 3, v44
	global_load_dwordx4 v[4:7], v[160:161], off
	v_lshl_add_u64 v[0:1], s[10:11], 0, v[0:1]
	v_lshl_add_u64 v[12:13], s[94:95], 0, v[12:13]
	v_lshl_add_u64 v[16:17], s[10:11], 0, v[16:17]
	v_ashrrev_i32_e32 v21, 31, v20
	v_ashrrev_i32_e32 v25, 31, v24
	v_subrev_u32_e32 v32, s38, v45
	v_lshl_add_u64 v[0:1], v[0:1], 0, v[2:3]
	v_lshl_add_u64 v[162:163], v[12:13], 0, v[2:3]
	v_lshl_add_u64 v[152:153], v[16:17], 0, v[2:3]
	v_lshlrev_b64 v[20:21], 11, v[20:21]
	v_lshlrev_b64 v[24:25], 11, v[24:25]
	v_add_u32_e32 v28, s12, v45
	v_add_u32_e32 v32, s36, v32
	global_load_dwordx4 v[8:11], v[0:1], off
	global_load_dwordx4 v[12:15], v[162:163], off
	global_load_dwordx4 v[16:19], v[152:153], off
	v_lshl_add_u64 v[20:21], s[94:95], 0, v[20:21]
	v_lshl_add_u64 v[24:25], s[10:11], 0, v[24:25]
	v_ashrrev_i32_e32 v29, 31, v28
	v_ashrrev_i32_e32 v33, 31, v32
	v_lshl_add_u64 v[164:165], v[20:21], 0, v[2:3]
	v_lshl_add_u64 v[154:155], v[24:25], 0, v[2:3]
	v_lshlrev_b64 v[28:29], 11, v[28:29]
	v_lshlrev_b64 v[32:33], 11, v[32:33]
	global_load_dwordx4 v[20:23], v[164:165], off
	global_load_dwordx4 v[24:27], v[154:155], off
	v_lshl_add_u64 v[28:29], s[94:95], 0, v[28:29]
	v_lshl_add_u64 v[32:33], s[10:11], 0, v[32:33]
	v_lshl_add_u64 v[166:167], v[28:29], 0, v[2:3]
	v_lshl_add_u64 v[156:157], v[32:33], 0, v[2:3]
	global_load_dwordx4 v[28:31], v[166:167], off
	global_load_dwordx4 v[32:35], v[156:157], off
	v_mul_lo_u32 v38, v38, s6
	v_add3_u32 v46, 0, v38, v2
	global_load_dwordx4 v[96:99], v[160:161], off offset:128
	global_load_dwordx4 v[92:95], v[0:1], off offset:128
	global_load_dwordx4 v[88:91], v[162:163], off offset:128
	global_load_dwordx4 v[84:87], v[152:153], off offset:128
	global_load_dwordx4 v[80:83], v[164:165], off offset:128
	global_load_dwordx4 v[76:79], v[154:155], off offset:128
	global_load_dwordx4 v[72:75], v[166:167], off offset:128
	global_load_dwordx4 v[68:71], v[156:157], off offset:128
	v_and_b32_e32 v37, 31, v151
	v_bfe_u32 v148, v151, 5, 1
	v_and_b32_e32 v36, 64, v151
	v_lshlrev_b32_e32 v39, 3, v151
	s_lshl_b64 s[40:41], s[12:13], 1
	s_add_u32 s40, s39, s40
	v_and_b32_e32 v202, 63, v151
	s_addc_u32 s41, s42, s41
	v_and_b32_e32 v205, 63, v151
	v_and_b32_e32 v204, 63, v151
	v_and_b32_e32 v203, 63, v151
	s_waitcnt vmcnt(15)
	ds_write_b128 v46, v[4:7]
	v_mul_lo_u32 v4, v41, s6
	v_add3_u32 v5, 0, v4, v2
	s_waitcnt vmcnt(14)
	ds_write_b128 v46, v[8:11] offset:36864
	s_waitcnt vmcnt(13)
	ds_write_b128 v5, v[12:15]
	s_waitcnt vmcnt(12)
	ds_write_b128 v5, v[16:19] offset:36864
	v_mul_lo_u32 v5, v43, s6
	v_add3_u32 v6, 0, v5, v2
	v_lshlrev_b32_e32 v8, 4, v148
	s_waitcnt vmcnt(11)
	ds_write_b128 v6, v[20:23]
	s_waitcnt vmcnt(10)
	ds_write_b128 v6, v[24:27] offset:36864
	v_mul_lo_u32 v6, v45, s6
	v_add3_u32 v7, 0, v6, v2
	s_waitcnt vmcnt(9)
	ds_write_b128 v7, v[28:31]
	s_waitcnt vmcnt(8)
	ds_write_b128 v7, v[32:35] offset:36864
	s_waitcnt lgkmcnt(0)
	s_barrier
	global_load_dwordx4 v[128:131], v[160:161], off offset:256
	global_load_dwordx4 v[124:127], v[0:1], off offset:256
	global_load_dwordx4 v[120:123], v[162:163], off offset:256
	global_load_dwordx4 v[116:119], v[152:153], off offset:256
	global_load_dwordx4 v[112:115], v[164:165], off offset:256
	global_load_dwordx4 v[108:111], v[154:155], off offset:256
	global_load_dwordx4 v[104:107], v[166:167], off offset:256
	global_load_dwordx4 v[100:103], v[156:157], off offset:256
	v_ashrrev_i32_e32 v7, 1, v151
	v_and_b32_e32 v190, 0xffffffc0, v7
	v_or_b32_e32 v7, v190, v37
	v_mul_lo_u32 v7, v7, s6
	v_add3_u32 v201, 0, v7, v8
	v_and_b32_e32 v7, 0x5f, v151
	v_mul_u32_u24_e32 v7, 0x90, v7
	v_add3_u32 v200, 0, v7, v8
	v_add_u32_e32 v7, 0, v2
	v_or_b32_e32 v2, 0x80, v37
	v_add_u32_e32 v9, v2, v190
	v_or_b32_e32 v2, v2, v36
	v_mul_lo_u32 v9, v9, s6
	v_mul_u32_u24_e32 v2, 0x90, v2
	v_add3_u32 v192, 0, v9, v8
	v_add3_u32 v191, 0, v2, v8
	v_lshrrev_b32_e32 v8, 6, v151
	v_lshlrev_b32_e32 v8, 5, v8
	v_lshlrev_b32_e32 v2, 1, v8
	v_mad_u32_u24 v8, v8, s6, 0
	v_lshl_add_u64 v[158:159], s[40:41], 0, v[2:3]
	v_add_u32_e32 v198, v7, v38
	v_lshl_add_u32 v199, v202, 1, v8
	v_add_u32_e32 v196, v7, v4
	v_lshl_add_u32 v197, v205, 1, v8
	v_add_u32_e32 v194, v7, v5
	v_lshl_add_u32 v195, v204, 1, v8
	v_add_u32_e32 v2, v7, v6
	v_lshl_add_u32 v193, v203, 1, v8
	ds_read_b128 v[4:7], v201 offset:4608
	ds_read_b128 v[8:11], v200 offset:41472
	ds_read_b128 v[12:15], v201
	ds_read_b128 v[132:135], v201 offset:32
	ds_read_b128 v[136:139], v201 offset:4640
	ds_read_b128 v[16:19], v200 offset:36864
	ds_read_b128 v[140:143], v200 offset:36896
	ds_read_b128 v[144:147], v200 offset:41504
	s_waitcnt lgkmcnt(2)
; #define MFMA(a, b, c) __builtin_amdgcn_mfma_f32_32x32x16_bf16((a), (b), (c), 0, 0, 0)
; template <class Epi, class ColV>
; DI void gemm_tile(const bf16_t* __restrict__ A, int lda, const bf16_t* __restrict__ Bt, int ldb, int K, int m0, int n0, unsigned char* smem, Epi epi, ColV colv, const bf16_t* __restrict__ HYT = nullptr) {
;     ...
;     auto step = [&](int kt, u32x4 (&ldset)[8], const u32x4 (&stset)[8]) {
;         const int buf = kt & 1;
;         if (kt + 2 < nk) gload(ldset, kt + 2);
;         const bf16_t* Ab = As + (buf * 128 + 64 * wr + li) * LS + 8 * lh;
;         const bf16_t* Bb = Bs + (buf * 128 + 64 * wc + li) * LS + 8 * lh;
;         bf16x8 fa[2][2], fb[2][2], ga[2][2], gb[2][2];
; #pragma unroll
;         for (int k2 = 0; k2 < 2; ++k2) { fa[k2][0] = ld8(Ab + 16 * k2); fa[k2][1] = ld8(Ab + 32 * LS + 16 * k2); fb[k2][0] = ld8(Bb + 16 * k2); fb[k2][1] = ld8(Bb + 32 * LS + 16 * k2); }
;         __builtin_amdgcn_sched_barrier(0);
; #pragma unroll
;         for (int k2 = 0; k2 < 2; ++k2) {
;             acc[0][0] = MFMA(fa[k2][0], fb[k2][0], acc[0][0]); acc[0][1] = MFMA(fa[k2][0], fb[k2][1], acc[0][1]);
;             acc[1][0] = MFMA(fa[k2][1], fb[k2][0], acc[1][0]); acc[1][1] = MFMA(fa[k2][1], fb[k2][1], acc[1][1]);
;         }
; #pragma unroll
;         for (int k2 = 0; k2 < 2; ++k2) { const int ks = 2 + k2; ga[k2][0] = ld8(Ab + 16 * ks); ga[k2][1] = ld8(Ab + 32 * LS + 16 * ks); gb[k2][0] = ld8(Bb + 16 * ks); gb[k2][1] = ld8(Bb + 32 * LS + 16 * ks); }
; #pragma unroll
;         for (int k2 = 0; k2 < 2; ++k2) {
;             acc[0][0] = MFMA(ga[k2][0], gb[k2][0], acc[0][0]); acc[0][1] = MFMA(ga[k2][0], gb[k2][1], acc[0][1]);
;             acc[1][0] = MFMA(ga[k2][1], gb[k2][0], acc[1][0]); acc[1][1] = MFMA(ga[k2][1], gb[k2][1], acc[1][1]);
;         }
;         if (kt + 1 < nk) sstore(stset, buf ^ 1, kt + 1);
; #pragma unroll
;         for (int i = 0; i < 8; ++i) { __builtin_amdgcn_sched_group_barrier(0x008, 1, 0); __builtin_amdgcn_sched_group_barrier(0x100, 1, 0); }
; #pragma unroll
;         for (int i = 0; i < 8; ++i) { __builtin_amdgcn_sched_group_barrier(0x008, 1, 0); __builtin_amdgcn_sched_group_barrier(0x200, 1, 0); }
;         __builtin_amdgcn_sched_barrier(0);
;         __syncthreads();
	v_mfma_f32_32x32x16_bf16 v[52:67], v[12:15], v[16:19], 0
	ds_read_b128 v[174:177], v201 offset:4704
	v_mfma_f32_32x32x16_bf16 v[36:51], v[12:15], v[8:11], 0
	ds_read_b128 v[178:181], v200 offset:36928
	v_mfma_f32_32x32x16_bf16 v[20:35], v[4:7], v[16:19], 0
	ds_read_b128 v[206:209], v200 offset:36960
	v_mfma_f32_32x32x16_bf16 v[4:19], v[4:7], v[8:11], 0
	ds_read_b128 v[210:213], v200 offset:41568
	s_waitcnt lgkmcnt(5)
	v_mfma_f32_32x32x16_bf16 v[52:67], v[132:135], v[140:143], v[52:67]
	s_waitcnt lgkmcnt(4)
	v_mfma_f32_32x32x16_bf16 v[36:51], v[132:135], v[144:147], v[36:51]
	v_mfma_f32_32x32x16_bf16 v[4:19], v[136:139], v[144:147], v[4:19]
	ds_read_b128 v[144:147], v201 offset:96
	ds_read_b128 v[132:135], v201 offset:4672
	v_mfma_f32_32x32x16_bf16 v[20:35], v[136:139], v[140:143], v[20:35]
	ds_read_b128 v[140:143], v201 offset:64
	ds_read_b128 v[136:139], v200 offset:41536
	s_waitcnt lgkmcnt(1)
	v_mfma_f32_32x32x16_bf16 v[52:67], v[140:143], v[178:181], v[52:67]
	s_waitcnt vmcnt(15)
	ds_write_b128 v198, v[96:99] offset:18432
	s_waitcnt lgkmcnt(1)
	v_mfma_f32_32x32x16_bf16 v[36:51], v[140:143], v[136:139], v[36:51]
	s_waitcnt vmcnt(14)
	ds_write_b128 v198, v[92:95] offset:55296
	v_mfma_f32_32x32x16_bf16 v[20:35], v[132:135], v[178:181], v[20:35]
	s_waitcnt vmcnt(13)
	ds_write_b128 v196, v[88:91] offset:18432
	v_mfma_f32_32x32x16_bf16 v[4:19], v[132:135], v[136:139], v[4:19]
	s_waitcnt vmcnt(12)
	ds_write_b128 v196, v[84:87] offset:55296
	v_mfma_f32_32x32x16_bf16 v[52:67], v[144:147], v[206:209], v[52:67]
	s_waitcnt vmcnt(11)
	ds_write_b128 v194, v[80:83] offset:18432
	v_mfma_f32_32x32x16_bf16 v[36:51], v[144:147], v[210:213], v[36:51]
	s_waitcnt vmcnt(10)
	ds_write_b128 v194, v[76:79] offset:55296
	v_mfma_f32_32x32x16_bf16 v[20:35], v[174:177], v[206:209], v[20:35]
	s_waitcnt vmcnt(9)
	ds_write_b128 v2, v[72:75] offset:18432
	v_mfma_f32_32x32x16_bf16 v[4:19], v[174:177], v[210:213], v[4:19]
	s_waitcnt vmcnt(8)
	ds_write_b128 v2, v[68:71] offset:55296
	s_waitcnt lgkmcnt(0)
	s_barrier
	global_load_dwordx4 v[144:147], v[160:161], off offset:384
	global_load_dwordx4 v[140:143], v[0:1], off offset:384
	global_load_dwordx4 v[136:139], v[162:163], off offset:384
	global_load_dwordx4 v[132:135], v[152:153], off offset:384
	global_load_dwordx4 v[92:95], v[164:165], off offset:384
	global_load_dwordx4 v[84:87], v[154:155], off offset:384
	global_load_dwordx4 v[76:79], v[166:167], off offset:384
	global_load_dwordx4 v[68:71], v[156:157], off offset:384
	ds_read_b128 v[72:75], v192
	ds_read_b128 v[80:83], v192 offset:32
	ds_read_b128 v[88:91], v192 offset:4608
	ds_read_b128 v[96:99], v192 offset:4640
	ds_read_b128 v[174:177], v191 offset:36864
	ds_read_b128 v[178:181], v191 offset:36896
	ds_read_b128 v[206:209], v191 offset:41472
	ds_read_b128 v[210:213], v191 offset:41504
	s_waitcnt lgkmcnt(3)
	v_mfma_f32_32x32x16_bf16 v[52:67], v[72:75], v[174:177], v[52:67]
	s_waitcnt lgkmcnt(1)
	v_mfma_f32_32x32x16_bf16 v[36:51], v[72:75], v[206:209], v[36:51]
	v_mfma_f32_32x32x16_bf16 v[4:19], v[88:91], v[206:209], v[4:19]
	s_waitcnt lgkmcnt(0)
	v_mfma_f32_32x32x16_bf16 v[36:51], v[80:83], v[210:213], v[36:51]
	v_mfma_f32_32x32x16_bf16 v[4:19], v[96:99], v[210:213], v[4:19]
	ds_read_b128 v[210:213], v191 offset:41568
	ds_read_b128 v[72:75], v192 offset:4672
	v_mfma_f32_32x32x16_bf16 v[20:35], v[88:91], v[174:177], v[20:35]
	ds_read_b128 v[174:177], v192 offset:4704
	ds_read_b128 v[88:91], v192 offset:64
	v_mfma_f32_32x32x16_bf16 v[52:67], v[80:83], v[178:181], v[52:67]
	ds_read_b128 v[206:209], v191 offset:36960
	ds_read_b128 v[80:83], v191 offset:41536
	v_mfma_f32_32x32x16_bf16 v[20:35], v[96:99], v[178:181], v[20:35]
	ds_read_b128 v[178:181], v191 offset:36928
	ds_read_b128 v[96:99], v192 offset:96
	s_waitcnt lgkmcnt(1)
	v_mfma_f32_32x32x16_bf16 v[52:67], v[88:91], v[178:181], v[52:67]
	s_waitcnt vmcnt(15)
	ds_write_b128 v198, v[128:131]
	v_mfma_f32_32x32x16_bf16 v[36:51], v[88:91], v[80:83], v[36:51]
	s_waitcnt vmcnt(14)
	ds_write_b128 v198, v[124:127] offset:36864
	v_mfma_f32_32x32x16_bf16 v[20:35], v[72:75], v[178:181], v[20:35]
	s_waitcnt vmcnt(13)
	ds_write_b128 v196, v[120:123]
	v_mfma_f32_32x32x16_bf16 v[4:19], v[72:75], v[80:83], v[4:19]
	s_waitcnt vmcnt(12)
	ds_write_b128 v196, v[116:119] offset:36864
	s_waitcnt lgkmcnt(4)
	v_mfma_f32_32x32x16_bf16 v[52:67], v[96:99], v[206:209], v[52:67]
	s_waitcnt vmcnt(11)
	ds_write_b128 v194, v[112:115]
	v_mfma_f32_32x32x16_bf16 v[36:51], v[96:99], v[210:213], v[36:51]
	s_waitcnt vmcnt(10)
	ds_write_b128 v194, v[108:111] offset:36864
	v_mfma_f32_32x32x16_bf16 v[20:35], v[174:177], v[206:209], v[20:35]
	s_waitcnt vmcnt(9)
	ds_write_b128 v2, v[104:107]
	v_mfma_f32_32x32x16_bf16 v[4:19], v[174:177], v[210:213], v[4:19]
	s_waitcnt vmcnt(8)
	ds_write_b128 v2, v[100:103] offset:36864
	s_waitcnt lgkmcnt(0)
	s_barrier
; #define MFMA(a, b, c) __builtin_amdgcn_mfma_f32_32x32x16_bf16((a), (b), (c), 0, 0, 0)
; template <class Epi, class ColV>
; DI void gemm_tile(const bf16_t* __restrict__ A, int lda, const bf16_t* __restrict__ Bt, int ldb, int K, int m0, int n0, unsigned char* smem, Epi epi, ColV colv, const bf16_t* __restrict__ HYT = nullptr) {
;     ...
;     auto step = [&](int kt, u32x4 (&ldset)[8], const u32x4 (&stset)[8]) {
;         const int buf = kt & 1;
;         if (kt + 2 < nk) gload(ldset, kt + 2);
;         const bf16_t* Ab = As + (buf * 128 + 64 * wr + li) * LS + 8 * lh;
;         const bf16_t* Bb = Bs + (buf * 128 + 64 * wc + li) * LS + 8 * lh;
;         bf16x8 fa[2][2], fb[2][2], ga[2][2], gb[2][2];
; #pragma unroll
;         for (int k2 = 0; k2 < 2; ++k2) { fa[k2][0] = ld8(Ab + 16 * k2); fa[k2][1] = ld8(Ab + 32 * LS + 16 * k2); fb[k2][0] = ld8(Bb + 16 * k2); fb[k2][1] = ld8(Bb + 32 * LS + 16 * k2); }
;         __builtin_amdgcn_sched_barrier(0);
; #pragma unroll
;         for (int k2 = 0; k2 < 2; ++k2) {
;             acc[0][0] = MFMA(fa[k2][0], fb[k2][0], acc[0][0]); acc[0][1] = MFMA(fa[k2][0], fb[k2][1], acc[0][1]);
;             acc[1][0] = MFMA(fa[k2][1], fb[k2][0], acc[1][0]); acc[1][1] = MFMA(fa[k2][1], fb[k2][1], acc[1][1]);
;         }
; #pragma unroll
;         for (int k2 = 0; k2 < 2; ++k2) { const int ks = 2 + k2; ga[k2][0] = ld8(Ab + 16 * ks); ga[k2][1] = ld8(Ab + 32 * LS + 16 * ks); gb[k2][0] = ld8(Bb + 16 * ks); gb[k2][1] = ld8(Bb + 32 * LS + 16 * ks); }
; #pragma unroll
;         for (int k2 = 0; k2 < 2; ++k2) {
;             acc[0][0] = MFMA(ga[k2][0], gb[k2][0], acc[0][0]); acc[0][1] = MFMA(ga[k2][0], gb[k2][1], acc[0][1]);
;             acc[1][0] = MFMA(ga[k2][1], gb[k2][0], acc[1][0]); acc[1][1] = MFMA(ga[k2][1], gb[k2][1], acc[1][1]);
;         }
;         if (kt + 1 < nk) sstore(stset, buf ^ 1, kt + 1);
; #pragma unroll
;         for (int i = 0; i < 8; ++i) { __builtin_amdgcn_sched_group_barrier(0x008, 1, 0); __builtin_amdgcn_sched_group_barrier(0x100, 1, 0); }
; #pragma unroll
;         for (int i = 0; i < 8; ++i) { __builtin_amdgcn_sched_group_barrier(0x008, 1, 0); __builtin_amdgcn_sched_group_barrier(0x200, 1, 0); }
;         __builtin_amdgcn_sched_barrier(0);
;         __syncthreads();
	global_load_dwordx4 v[124:127], v[160:161], off offset:512
	global_load_dwordx4 v[116:119], v[0:1], off offset:512
	global_load_dwordx4 v[108:111], v[162:163], off offset:512
	global_load_dwordx4 v[100:103], v[152:153], off offset:512
	global_load_dwordx4 v[96:99], v[164:165], off offset:512
	global_load_dwordx4 v[88:91], v[154:155], off offset:512
	global_load_dwordx4 v[80:83], v[166:167], off offset:512
	global_load_dwordx4 v[72:75], v[156:157], off offset:512
	ds_read_b128 v[104:107], v201
	ds_read_b128 v[112:115], v201 offset:32
	ds_read_b128 v[120:123], v201 offset:4608
	ds_read_b128 v[128:131], v201 offset:4640
	ds_read_b128 v[174:177], v200 offset:36864
	ds_read_b128 v[178:181], v200 offset:36896
	ds_read_b128 v[206:209], v200 offset:41472
	ds_read_b128 v[210:213], v200 offset:41504
	s_waitcnt lgkmcnt(3)
	v_mfma_f32_32x32x16_bf16 v[52:67], v[104:107], v[174:177], v[52:67]
	s_waitcnt lgkmcnt(1)
	v_mfma_f32_32x32x16_bf16 v[36:51], v[104:107], v[206:209], v[36:51]
	v_mfma_f32_32x32x16_bf16 v[4:19], v[120:123], v[206:209], v[4:19]
	s_waitcnt lgkmcnt(0)
	v_mfma_f32_32x32x16_bf16 v[36:51], v[112:115], v[210:213], v[36:51]
	v_mfma_f32_32x32x16_bf16 v[4:19], v[128:131], v[210:213], v[4:19]
	ds_read_b128 v[210:213], v200 offset:41568
	ds_read_b128 v[104:107], v201 offset:4672
	v_mfma_f32_32x32x16_bf16 v[20:35], v[120:123], v[174:177], v[20:35]
	ds_read_b128 v[174:177], v201 offset:4704
	ds_read_b128 v[120:123], v201 offset:64
	v_mfma_f32_32x32x16_bf16 v[52:67], v[112:115], v[178:181], v[52:67]
	ds_read_b128 v[206:209], v200 offset:36960
	ds_read_b128 v[112:115], v200 offset:41536
	v_mfma_f32_32x32x16_bf16 v[20:35], v[128:131], v[178:181], v[20:35]
	ds_read_b128 v[178:181], v200 offset:36928
	ds_read_b128 v[128:131], v201 offset:96
	s_waitcnt lgkmcnt(1)
	v_mfma_f32_32x32x16_bf16 v[52:67], v[120:123], v[178:181], v[52:67]
	s_waitcnt vmcnt(15)
	ds_write_b128 v198, v[144:147] offset:18432
	v_mfma_f32_32x32x16_bf16 v[36:51], v[120:123], v[112:115], v[36:51]
	s_waitcnt vmcnt(14)
	ds_write_b128 v198, v[140:143] offset:55296
	v_mfma_f32_32x32x16_bf16 v[20:35], v[104:107], v[178:181], v[20:35]
	s_waitcnt vmcnt(13)
	ds_write_b128 v196, v[136:139] offset:18432
	v_mfma_f32_32x32x16_bf16 v[4:19], v[104:107], v[112:115], v[4:19]
	s_waitcnt vmcnt(12)
	ds_write_b128 v196, v[132:135] offset:55296
	s_waitcnt lgkmcnt(4)
	v_mfma_f32_32x32x16_bf16 v[52:67], v[128:131], v[206:209], v[52:67]
	s_waitcnt vmcnt(11)
	ds_write_b128 v194, v[92:95] offset:18432
	v_mfma_f32_32x32x16_bf16 v[36:51], v[128:131], v[210:213], v[36:51]
	s_waitcnt vmcnt(10)
	ds_write_b128 v194, v[84:87] offset:55296
	v_mfma_f32_32x32x16_bf16 v[20:35], v[174:177], v[206:209], v[20:35]
	s_waitcnt vmcnt(9)
	ds_write_b128 v2, v[76:79] offset:18432
	v_mfma_f32_32x32x16_bf16 v[4:19], v[174:177], v[210:213], v[4:19]
	s_waitcnt vmcnt(8)
	ds_write_b128 v2, v[68:71] offset:55296
	s_waitcnt lgkmcnt(0)
	s_barrier
	global_load_dwordx4 v[128:131], v[160:161], off offset:640
	global_load_dwordx4 v[120:123], v[0:1], off offset:640
	global_load_dwordx4 v[112:115], v[162:163], off offset:640
	global_load_dwordx4 v[104:107], v[152:153], off offset:640
	global_load_dwordx4 v[92:95], v[164:165], off offset:640
	global_load_dwordx4 v[84:87], v[154:155], off offset:640
	global_load_dwordx4 v[76:79], v[166:167], off offset:640
	global_load_dwordx4 v[68:71], v[156:157], off offset:640
	ds_read_b128 v[132:135], v192
	ds_read_b128 v[136:139], v192 offset:32
	ds_read_b128 v[140:143], v192 offset:4608
	ds_read_b128 v[144:147], v192 offset:4640
	ds_read_b128 v[174:177], v191 offset:36864
	ds_read_b128 v[178:181], v191 offset:36896
	ds_read_b128 v[206:209], v191 offset:41472
	ds_read_b128 v[210:213], v191 offset:41504
	s_waitcnt lgkmcnt(3)
	v_mfma_f32_32x32x16_bf16 v[52:67], v[132:135], v[174:177], v[52:67]
	s_waitcnt lgkmcnt(1)
	v_mfma_f32_32x32x16_bf16 v[36:51], v[132:135], v[206:209], v[36:51]
	v_mfma_f32_32x32x16_bf16 v[4:19], v[140:143], v[206:209], v[4:19]
	s_waitcnt lgkmcnt(0)
	v_mfma_f32_32x32x16_bf16 v[36:51], v[136:139], v[210:213], v[36:51]
	v_mfma_f32_32x32x16_bf16 v[4:19], v[144:147], v[210:213], v[4:19]
	ds_read_b128 v[210:213], v191 offset:41568
	ds_read_b128 v[132:135], v192 offset:4672
	v_mfma_f32_32x32x16_bf16 v[20:35], v[140:143], v[174:177], v[20:35]
	ds_read_b128 v[174:177], v192 offset:4704
	ds_read_b128 v[140:143], v192 offset:64
	v_mfma_f32_32x32x16_bf16 v[52:67], v[136:139], v[178:181], v[52:67]
	ds_read_b128 v[206:209], v191 offset:36960
	ds_read_b128 v[136:139], v191 offset:41536
	v_mfma_f32_32x32x16_bf16 v[20:35], v[144:147], v[178:181], v[20:35]
	ds_read_b128 v[178:181], v191 offset:36928
	ds_read_b128 v[144:147], v192 offset:96
	s_waitcnt lgkmcnt(1)
	v_mfma_f32_32x32x16_bf16 v[52:67], v[140:143], v[178:181], v[52:67]
	s_waitcnt vmcnt(15)
	ds_write_b128 v198, v[124:127]
	v_mfma_f32_32x32x16_bf16 v[36:51], v[140:143], v[136:139], v[36:51]
	s_waitcnt vmcnt(14)
	ds_write_b128 v198, v[116:119] offset:36864
	v_mfma_f32_32x32x16_bf16 v[20:35], v[132:135], v[178:181], v[20:35]
	s_waitcnt vmcnt(13)
	ds_write_b128 v196, v[108:111]
	v_mfma_f32_32x32x16_bf16 v[4:19], v[132:135], v[136:139], v[4:19]
	s_waitcnt vmcnt(12)
	ds_write_b128 v196, v[100:103] offset:36864
	s_waitcnt lgkmcnt(4)
	v_mfma_f32_32x32x16_bf16 v[52:67], v[144:147], v[206:209], v[52:67]
	s_waitcnt vmcnt(11)
	ds_write_b128 v194, v[96:99]
	v_mfma_f32_32x32x16_bf16 v[36:51], v[144:147], v[210:213], v[36:51]
	s_waitcnt vmcnt(10)
	ds_write_b128 v194, v[88:91] offset:36864
	v_mfma_f32_32x32x16_bf16 v[20:35], v[174:177], v[206:209], v[20:35]
	s_waitcnt vmcnt(9)
	ds_write_b128 v2, v[80:83]
	v_mfma_f32_32x32x16_bf16 v[4:19], v[174:177], v[210:213], v[4:19]
	s_waitcnt vmcnt(8)
	ds_write_b128 v2, v[72:75] offset:36864
	s_waitcnt lgkmcnt(0)
	s_barrier
; #define MFMA(a, b, c) __builtin_amdgcn_mfma_f32_32x32x16_bf16((a), (b), (c), 0, 0, 0)
; template <class Epi, class ColV>
; DI void gemm_tile(const bf16_t* __restrict__ A, int lda, const bf16_t* __restrict__ Bt, int ldb, int K, int m0, int n0, unsigned char* smem, Epi epi, ColV colv, const bf16_t* __restrict__ HYT = nullptr) {
;     ...
;     auto step = [&](int kt, u32x4 (&ldset)[8], const u32x4 (&stset)[8]) {
;         const int buf = kt & 1;
;         if (kt + 2 < nk) gload(ldset, kt + 2);
;         const bf16_t* Ab = As + (buf * 128 + 64 * wr + li) * LS + 8 * lh;
;         const bf16_t* Bb = Bs + (buf * 128 + 64 * wc + li) * LS + 8 * lh;
;         bf16x8 fa[2][2], fb[2][2], ga[2][2], gb[2][2];
; #pragma unroll
;         for (int k2 = 0; k2 < 2; ++k2) { fa[k2][0] = ld8(Ab + 16 * k2); fa[k2][1] = ld8(Ab + 32 * LS + 16 * k2); fb[k2][0] = ld8(Bb + 16 * k2); fb[k2][1] = ld8(Bb + 32 * LS + 16 * k2); }
;         __builtin_amdgcn_sched_barrier(0);
; #pragma unroll
;         for (int k2 = 0; k2 < 2; ++k2) {
;             acc[0][0] = MFMA(fa[k2][0], fb[k2][0], acc[0][0]); acc[0][1] = MFMA(fa[k2][0], fb[k2][1], acc[0][1]);
;             acc[1][0] = MFMA(fa[k2][1], fb[k2][0], acc[1][0]); acc[1][1] = MFMA(fa[k2][1], fb[k2][1], acc[1][1]);
;         }
; #pragma unroll
;         for (int k2 = 0; k2 < 2; ++k2) { const int ks = 2 + k2; ga[k2][0] = ld8(Ab + 16 * ks); ga[k2][1] = ld8(Ab + 32 * LS + 16 * ks); gb[k2][0] = ld8(Bb + 16 * ks); gb[k2][1] = ld8(Bb + 32 * LS + 16 * ks); }
; #pragma unroll
;         for (int k2 = 0; k2 < 2; ++k2) {
;             acc[0][0] = MFMA(ga[k2][0], gb[k2][0], acc[0][0]); acc[0][1] = MFMA(ga[k2][0], gb[k2][1], acc[0][1]);
;             acc[1][0] = MFMA(ga[k2][1], gb[k2][0], acc[1][0]); acc[1][1] = MFMA(ga[k2][1], gb[k2][1], acc[1][1]);
;         }
;         if (kt + 1 < nk) sstore(stset, buf ^ 1, kt + 1);
; #pragma unroll
;         for (int i = 0; i < 8; ++i) { __builtin_amdgcn_sched_group_barrier(0x008, 1, 0); __builtin_amdgcn_sched_group_barrier(0x100, 1, 0); }
; #pragma unroll
;         for (int i = 0; i < 8; ++i) { __builtin_amdgcn_sched_group_barrier(0x008, 1, 0); __builtin_amdgcn_sched_group_barrier(0x200, 1, 0); }
;         __builtin_amdgcn_sched_barrier(0);
;         __syncthreads();
	global_load_dwordx4 v[124:127], v[160:161], off offset:768
	global_load_dwordx4 v[116:119], v[0:1], off offset:768
	global_load_dwordx4 v[108:111], v[162:163], off offset:768
	global_load_dwordx4 v[100:103], v[152:153], off offset:768
	global_load_dwordx4 v[96:99], v[164:165], off offset:768
	global_load_dwordx4 v[88:91], v[154:155], off offset:768
	global_load_dwordx4 v[80:83], v[166:167], off offset:768
	global_load_dwordx4 v[72:75], v[156:157], off offset:768
	ds_read_b128 v[132:135], v201
	ds_read_b128 v[136:139], v201 offset:32
	ds_read_b128 v[140:143], v201 offset:4608
	ds_read_b128 v[144:147], v201 offset:4640
	ds_read_b128 v[174:177], v200 offset:36864
	ds_read_b128 v[178:181], v200 offset:36896
	ds_read_b128 v[206:209], v200 offset:41472
	ds_read_b128 v[210:213], v200 offset:41504
	s_waitcnt lgkmcnt(3)
	v_mfma_f32_32x32x16_bf16 v[52:67], v[132:135], v[174:177], v[52:67]
	s_waitcnt lgkmcnt(1)
	v_mfma_f32_32x32x16_bf16 v[36:51], v[132:135], v[206:209], v[36:51]
	v_mfma_f32_32x32x16_bf16 v[4:19], v[140:143], v[206:209], v[4:19]
	s_waitcnt lgkmcnt(0)
	v_mfma_f32_32x32x16_bf16 v[36:51], v[136:139], v[210:213], v[36:51]
	v_mfma_f32_32x32x16_bf16 v[4:19], v[144:147], v[210:213], v[4:19]
	ds_read_b128 v[210:213], v200 offset:41568
	ds_read_b128 v[132:135], v201 offset:4672
	v_mfma_f32_32x32x16_bf16 v[20:35], v[140:143], v[174:177], v[20:35]
	ds_read_b128 v[174:177], v201 offset:4704
	ds_read_b128 v[140:143], v201 offset:64
	v_mfma_f32_32x32x16_bf16 v[52:67], v[136:139], v[178:181], v[52:67]
	ds_read_b128 v[206:209], v200 offset:36960
	ds_read_b128 v[136:139], v200 offset:41536
	v_mfma_f32_32x32x16_bf16 v[20:35], v[144:147], v[178:181], v[20:35]
	ds_read_b128 v[178:181], v200 offset:36928
	ds_read_b128 v[144:147], v201 offset:96
	s_waitcnt lgkmcnt(1)
	v_mfma_f32_32x32x16_bf16 v[52:67], v[140:143], v[178:181], v[52:67]
	s_waitcnt vmcnt(15)
	ds_write_b128 v198, v[128:131] offset:18432
	v_mfma_f32_32x32x16_bf16 v[36:51], v[140:143], v[136:139], v[36:51]
	s_waitcnt vmcnt(14)
	ds_write_b128 v198, v[120:123] offset:55296
	v_mfma_f32_32x32x16_bf16 v[20:35], v[132:135], v[178:181], v[20:35]
	s_waitcnt vmcnt(13)
	ds_write_b128 v196, v[112:115] offset:18432
	v_mfma_f32_32x32x16_bf16 v[4:19], v[132:135], v[136:139], v[4:19]
	s_waitcnt vmcnt(12)
	ds_write_b128 v196, v[104:107] offset:55296
	s_waitcnt lgkmcnt(4)
	v_mfma_f32_32x32x16_bf16 v[52:67], v[144:147], v[206:209], v[52:67]
	s_waitcnt vmcnt(11)
	ds_write_b128 v194, v[92:95] offset:18432
	v_mfma_f32_32x32x16_bf16 v[36:51], v[144:147], v[210:213], v[36:51]
	s_waitcnt vmcnt(10)
	ds_write_b128 v194, v[84:87] offset:55296
	v_mfma_f32_32x32x16_bf16 v[20:35], v[174:177], v[206:209], v[20:35]
	s_waitcnt vmcnt(9)
	ds_write_b128 v2, v[76:79] offset:18432
	v_mfma_f32_32x32x16_bf16 v[4:19], v[174:177], v[210:213], v[4:19]
	s_waitcnt vmcnt(8)
	ds_write_b128 v2, v[68:71] offset:55296
	s_waitcnt lgkmcnt(0)
	s_barrier
	global_load_dwordx4 v[128:131], v[160:161], off offset:896
	global_load_dwordx4 v[120:123], v[0:1], off offset:896
	global_load_dwordx4 v[112:115], v[162:163], off offset:896
	global_load_dwordx4 v[104:107], v[152:153], off offset:896
	global_load_dwordx4 v[92:95], v[164:165], off offset:896
	global_load_dwordx4 v[84:87], v[154:155], off offset:896
	global_load_dwordx4 v[76:79], v[166:167], off offset:896
	global_load_dwordx4 v[68:71], v[156:157], off offset:896
	ds_read_b128 v[132:135], v192
	ds_read_b128 v[136:139], v192 offset:32
	ds_read_b128 v[140:143], v192 offset:4608
	ds_read_b128 v[144:147], v192 offset:4640
	ds_read_b128 v[174:177], v191 offset:36864
	ds_read_b128 v[178:181], v191 offset:36896
	ds_read_b128 v[206:209], v191 offset:41472
	ds_read_b128 v[210:213], v191 offset:41504
	s_waitcnt lgkmcnt(3)
	v_mfma_f32_32x32x16_bf16 v[52:67], v[132:135], v[174:177], v[52:67]
	s_waitcnt lgkmcnt(1)
	v_mfma_f32_32x32x16_bf16 v[36:51], v[132:135], v[206:209], v[36:51]
	v_mfma_f32_32x32x16_bf16 v[4:19], v[140:143], v[206:209], v[4:19]
	s_waitcnt lgkmcnt(0)
	v_mfma_f32_32x32x16_bf16 v[36:51], v[136:139], v[210:213], v[36:51]
	v_mfma_f32_32x32x16_bf16 v[4:19], v[144:147], v[210:213], v[4:19]
	ds_read_b128 v[210:213], v191 offset:41568
	ds_read_b128 v[132:135], v192 offset:4672
	v_mfma_f32_32x32x16_bf16 v[20:35], v[140:143], v[174:177], v[20:35]
	ds_read_b128 v[174:177], v192 offset:4704
	ds_read_b128 v[140:143], v192 offset:64
	v_mfma_f32_32x32x16_bf16 v[52:67], v[136:139], v[178:181], v[52:67]
	ds_read_b128 v[206:209], v191 offset:36960
	ds_read_b128 v[136:139], v191 offset:41536
	v_mfma_f32_32x32x16_bf16 v[20:35], v[144:147], v[178:181], v[20:35]
	ds_read_b128 v[178:181], v191 offset:36928
	ds_read_b128 v[144:147], v192 offset:96
	s_waitcnt lgkmcnt(1)
	v_mfma_f32_32x32x16_bf16 v[52:67], v[140:143], v[178:181], v[52:67]
	s_waitcnt vmcnt(15)
	ds_write_b128 v198, v[124:127]
	v_mfma_f32_32x32x16_bf16 v[36:51], v[140:143], v[136:139], v[36:51]
	s_waitcnt vmcnt(14)
	ds_write_b128 v198, v[116:119] offset:36864
	v_mfma_f32_32x32x16_bf16 v[20:35], v[132:135], v[178:181], v[20:35]
	s_waitcnt vmcnt(13)
	ds_write_b128 v196, v[108:111]
	v_mfma_f32_32x32x16_bf16 v[4:19], v[132:135], v[136:139], v[4:19]
	s_waitcnt vmcnt(12)
	ds_write_b128 v196, v[100:103] offset:36864
	s_waitcnt lgkmcnt(4)
	v_mfma_f32_32x32x16_bf16 v[52:67], v[144:147], v[206:209], v[52:67]
	s_waitcnt vmcnt(11)
	ds_write_b128 v194, v[96:99]
	v_mfma_f32_32x32x16_bf16 v[36:51], v[144:147], v[210:213], v[36:51]
	s_waitcnt vmcnt(10)
	ds_write_b128 v194, v[88:91] offset:36864
	v_mfma_f32_32x32x16_bf16 v[20:35], v[174:177], v[206:209], v[20:35]
	s_waitcnt vmcnt(9)
	ds_write_b128 v2, v[80:83]
	v_mfma_f32_32x32x16_bf16 v[4:19], v[174:177], v[210:213], v[4:19]
	s_waitcnt vmcnt(8)
	ds_write_b128 v2, v[72:75] offset:36864
	s_waitcnt lgkmcnt(0)
	s_barrier
; #define MFMA(a, b, c) __builtin_amdgcn_mfma_f32_32x32x16_bf16((a), (b), (c), 0, 0, 0)
; template <class Epi, class ColV>
; DI void gemm_tile(const bf16_t* __restrict__ A, int lda, const bf16_t* __restrict__ Bt, int ldb, int K, int m0, int n0, unsigned char* smem, Epi epi, ColV colv, const bf16_t* __restrict__ HYT = nullptr) {
;     ...
;     auto step = [&](int kt, u32x4 (&ldset)[8], const u32x4 (&stset)[8]) {
;         const int buf = kt & 1;
;         if (kt + 2 < nk) gload(ldset, kt + 2);
;         const bf16_t* Ab = As + (buf * 128 + 64 * wr + li) * LS + 8 * lh;
;         const bf16_t* Bb = Bs + (buf * 128 + 64 * wc + li) * LS + 8 * lh;
;         bf16x8 fa[2][2], fb[2][2], ga[2][2], gb[2][2];
; #pragma unroll
;         for (int k2 = 0; k2 < 2; ++k2) { fa[k2][0] = ld8(Ab + 16 * k2); fa[k2][1] = ld8(Ab + 32 * LS + 16 * k2); fb[k2][0] = ld8(Bb + 16 * k2); fb[k2][1] = ld8(Bb + 32 * LS + 16 * k2); }
;         __builtin_amdgcn_sched_barrier(0);
; #pragma unroll
;         for (int k2 = 0; k2 < 2; ++k2) {
;             acc[0][0] = MFMA(fa[k2][0], fb[k2][0], acc[0][0]); acc[0][1] = MFMA(fa[k2][0], fb[k2][1], acc[0][1]);
;             acc[1][0] = MFMA(fa[k2][1], fb[k2][0], acc[1][0]); acc[1][1] = MFMA(fa[k2][1], fb[k2][1], acc[1][1]);
;         }
; #pragma unroll
;         for (int k2 = 0; k2 < 2; ++k2) { const int ks = 2 + k2; ga[k2][0] = ld8(Ab + 16 * ks); ga[k2][1] = ld8(Ab + 32 * LS + 16 * ks); gb[k2][0] = ld8(Bb + 16 * ks); gb[k2][1] = ld8(Bb + 32 * LS + 16 * ks); }
; #pragma unroll
;         for (int k2 = 0; k2 < 2; ++k2) {
;             acc[0][0] = MFMA(ga[k2][0], gb[k2][0], acc[0][0]); acc[0][1] = MFMA(ga[k2][0], gb[k2][1], acc[0][1]);
;             acc[1][0] = MFMA(ga[k2][1], gb[k2][0], acc[1][0]); acc[1][1] = MFMA(ga[k2][1], gb[k2][1], acc[1][1]);
;         }
;         if (kt + 1 < nk) sstore(stset, buf ^ 1, kt + 1);
; #pragma unroll
;         for (int i = 0; i < 8; ++i) { __builtin_amdgcn_sched_group_barrier(0x008, 1, 0); __builtin_amdgcn_sched_group_barrier(0x100, 1, 0); }
; #pragma unroll
;         for (int i = 0; i < 8; ++i) { __builtin_amdgcn_sched_group_barrier(0x008, 1, 0); __builtin_amdgcn_sched_group_barrier(0x200, 1, 0); }
;         __builtin_amdgcn_sched_barrier(0);
;         __syncthreads();
	global_load_dwordx4 v[132:135], v[160:161], off offset:1024
	global_load_dwordx4 v[124:127], v[0:1], off offset:1024
	global_load_dwordx4 v[108:111], v[162:163], off offset:1024
	global_load_dwordx4 v[100:103], v[152:153], off offset:1024
	global_load_dwordx4 v[96:99], v[164:165], off offset:1024
	global_load_dwordx4 v[88:91], v[154:155], off offset:1024
	global_load_dwordx4 v[80:83], v[166:167], off offset:1024
	global_load_dwordx4 v[72:75], v[156:157], off offset:1024
	ds_read_b128 v[116:119], v201
	ds_read_b128 v[136:139], v201 offset:32
	ds_read_b128 v[140:143], v201 offset:4608
	ds_read_b128 v[144:147], v201 offset:4640
	ds_read_b128 v[174:177], v200 offset:36864
	ds_read_b128 v[178:181], v200 offset:36896
	ds_read_b128 v[206:209], v200 offset:41472
	ds_read_b128 v[210:213], v200 offset:41504
	s_waitcnt lgkmcnt(3)
	v_mfma_f32_32x32x16_bf16 v[52:67], v[116:119], v[174:177], v[52:67]
	s_waitcnt lgkmcnt(1)
	v_mfma_f32_32x32x16_bf16 v[36:51], v[116:119], v[206:209], v[36:51]
	v_mfma_f32_32x32x16_bf16 v[4:19], v[140:143], v[206:209], v[4:19]
	s_waitcnt lgkmcnt(0)
	v_mfma_f32_32x32x16_bf16 v[36:51], v[136:139], v[210:213], v[36:51]
	v_mfma_f32_32x32x16_bf16 v[4:19], v[144:147], v[210:213], v[4:19]
	ds_read_b128 v[210:213], v200 offset:41568
	ds_read_b128 v[116:119], v201 offset:4672
	v_mfma_f32_32x32x16_bf16 v[20:35], v[140:143], v[174:177], v[20:35]
	ds_read_b128 v[174:177], v201 offset:4704
	ds_read_b128 v[140:143], v201 offset:64
	v_mfma_f32_32x32x16_bf16 v[52:67], v[136:139], v[178:181], v[52:67]
	ds_read_b128 v[206:209], v200 offset:36960
	ds_read_b128 v[136:139], v200 offset:41536
	v_mfma_f32_32x32x16_bf16 v[20:35], v[144:147], v[178:181], v[20:35]
	ds_read_b128 v[178:181], v200 offset:36928
	ds_read_b128 v[144:147], v201 offset:96
	s_waitcnt lgkmcnt(1)
	v_mfma_f32_32x32x16_bf16 v[52:67], v[140:143], v[178:181], v[52:67]
	s_waitcnt vmcnt(15)
	ds_write_b128 v198, v[128:131] offset:18432
	v_mfma_f32_32x32x16_bf16 v[36:51], v[140:143], v[136:139], v[36:51]
	s_waitcnt vmcnt(14)
	ds_write_b128 v198, v[120:123] offset:55296
	v_mfma_f32_32x32x16_bf16 v[20:35], v[116:119], v[178:181], v[20:35]
	s_waitcnt vmcnt(13)
	ds_write_b128 v196, v[112:115] offset:18432
	v_mfma_f32_32x32x16_bf16 v[4:19], v[116:119], v[136:139], v[4:19]
	s_waitcnt vmcnt(12)
	ds_write_b128 v196, v[104:107] offset:55296
	s_waitcnt lgkmcnt(4)
	v_mfma_f32_32x32x16_bf16 v[52:67], v[144:147], v[206:209], v[52:67]
	s_waitcnt vmcnt(11)
	ds_write_b128 v194, v[92:95] offset:18432
	v_mfma_f32_32x32x16_bf16 v[36:51], v[144:147], v[210:213], v[36:51]
	s_waitcnt vmcnt(10)
	ds_write_b128 v194, v[84:87] offset:55296
	v_mfma_f32_32x32x16_bf16 v[20:35], v[174:177], v[206:209], v[20:35]
	s_waitcnt vmcnt(9)
	ds_write_b128 v2, v[76:79] offset:18432
	v_mfma_f32_32x32x16_bf16 v[4:19], v[174:177], v[210:213], v[4:19]
	s_waitcnt vmcnt(8)
	ds_write_b128 v2, v[68:71] offset:55296
	s_waitcnt lgkmcnt(0)
	s_barrier
	global_load_dwordx4 v[136:139], v[160:161], off offset:1152
	global_load_dwordx4 v[128:131], v[0:1], off offset:1152
	global_load_dwordx4 v[116:119], v[162:163], off offset:1152
	global_load_dwordx4 v[104:107], v[152:153], off offset:1152
	global_load_dwordx4 v[92:95], v[164:165], off offset:1152
	global_load_dwordx4 v[84:87], v[154:155], off offset:1152
	global_load_dwordx4 v[76:79], v[166:167], off offset:1152
	global_load_dwordx4 v[68:71], v[156:157], off offset:1152
	ds_read_b128 v[112:115], v192
	ds_read_b128 v[120:123], v192 offset:32
	ds_read_b128 v[140:143], v192 offset:4608
	ds_read_b128 v[144:147], v192 offset:4640
	ds_read_b128 v[174:177], v191 offset:36864
	ds_read_b128 v[178:181], v191 offset:36896
	ds_read_b128 v[206:209], v191 offset:41472
	ds_read_b128 v[210:213], v191 offset:41504
	s_waitcnt lgkmcnt(3)
	v_mfma_f32_32x32x16_bf16 v[52:67], v[112:115], v[174:177], v[52:67]
	s_waitcnt lgkmcnt(1)
	v_mfma_f32_32x32x16_bf16 v[36:51], v[112:115], v[206:209], v[36:51]
	v_mfma_f32_32x32x16_bf16 v[4:19], v[140:143], v[206:209], v[4:19]
	s_waitcnt lgkmcnt(0)
	v_mfma_f32_32x32x16_bf16 v[36:51], v[120:123], v[210:213], v[36:51]
	v_mfma_f32_32x32x16_bf16 v[4:19], v[144:147], v[210:213], v[4:19]
	ds_read_b128 v[210:213], v191 offset:41568
	ds_read_b128 v[112:115], v192 offset:4672
	v_mfma_f32_32x32x16_bf16 v[20:35], v[140:143], v[174:177], v[20:35]
	ds_read_b128 v[174:177], v192 offset:4704
	ds_read_b128 v[140:143], v192 offset:64
	v_mfma_f32_32x32x16_bf16 v[52:67], v[120:123], v[178:181], v[52:67]
	ds_read_b128 v[206:209], v191 offset:36960
	ds_read_b128 v[120:123], v191 offset:41536
	v_mfma_f32_32x32x16_bf16 v[20:35], v[144:147], v[178:181], v[20:35]
	ds_read_b128 v[178:181], v191 offset:36928
	ds_read_b128 v[144:147], v192 offset:96
	s_waitcnt lgkmcnt(1)
	v_mfma_f32_32x32x16_bf16 v[52:67], v[140:143], v[178:181], v[52:67]
	s_waitcnt vmcnt(15)
	ds_write_b128 v198, v[132:135]
	v_mfma_f32_32x32x16_bf16 v[36:51], v[140:143], v[120:123], v[36:51]
	s_waitcnt vmcnt(14)
	ds_write_b128 v198, v[124:127] offset:36864
	v_mfma_f32_32x32x16_bf16 v[20:35], v[112:115], v[178:181], v[20:35]
	s_waitcnt vmcnt(13)
	ds_write_b128 v196, v[108:111]
	v_mfma_f32_32x32x16_bf16 v[4:19], v[112:115], v[120:123], v[4:19]
	s_waitcnt vmcnt(12)
	ds_write_b128 v196, v[100:103] offset:36864
	s_waitcnt lgkmcnt(4)
	v_mfma_f32_32x32x16_bf16 v[52:67], v[144:147], v[206:209], v[52:67]
	s_waitcnt vmcnt(11)
	ds_write_b128 v194, v[96:99]
	v_mfma_f32_32x32x16_bf16 v[36:51], v[144:147], v[210:213], v[36:51]
	s_waitcnt vmcnt(10)
	ds_write_b128 v194, v[88:91] offset:36864
	v_mfma_f32_32x32x16_bf16 v[20:35], v[174:177], v[206:209], v[20:35]
	s_waitcnt vmcnt(9)
	ds_write_b128 v2, v[80:83]
	v_mfma_f32_32x32x16_bf16 v[4:19], v[174:177], v[210:213], v[4:19]
	s_waitcnt vmcnt(8)
	ds_write_b128 v2, v[72:75] offset:36864
	s_waitcnt lgkmcnt(0)
	s_barrier
; #define MFMA(a, b, c) __builtin_amdgcn_mfma_f32_32x32x16_bf16((a), (b), (c), 0, 0, 0)
; template <class Epi, class ColV>
; DI void gemm_tile(const bf16_t* __restrict__ A, int lda, const bf16_t* __restrict__ Bt, int ldb, int K, int m0, int n0, unsigned char* smem, Epi epi, ColV colv, const bf16_t* __restrict__ HYT = nullptr) {
;     ...
;             if (HYT && kt >= 12) r[i] = *(const u32x4*)(HYT + (size_t)((kt - 12) * 64 + (id >> 4)) * NT + m0 + (id & 15) * 8);
;     ...
;     auto step = [&](int kt, u32x4 (&ldset)[8], const u32x4 (&stset)[8]) {
;         const int buf = kt & 1;
;         if (kt + 2 < nk) gload(ldset, kt + 2);
;         const bf16_t* Ab = As + (buf * 128 + 64 * wr + li) * LS + 8 * lh;
;         const bf16_t* Bb = Bs + (buf * 128 + 64 * wc + li) * LS + 8 * lh;
;         bf16x8 fa[2][2], fb[2][2], ga[2][2], gb[2][2];
; #pragma unroll
;         for (int k2 = 0; k2 < 2; ++k2) { fa[k2][0] = ld8(Ab + 16 * k2); fa[k2][1] = ld8(Ab + 32 * LS + 16 * k2); fb[k2][0] = ld8(Bb + 16 * k2); fb[k2][1] = ld8(Bb + 32 * LS + 16 * k2); }
;         __builtin_amdgcn_sched_barrier(0);
; #pragma unroll
;         for (int k2 = 0; k2 < 2; ++k2) {
;             acc[0][0] = MFMA(fa[k2][0], fb[k2][0], acc[0][0]); acc[0][1] = MFMA(fa[k2][0], fb[k2][1], acc[0][1]);
;             acc[1][0] = MFMA(fa[k2][1], fb[k2][0], acc[1][0]); acc[1][1] = MFMA(fa[k2][1], fb[k2][1], acc[1][1]);
;         }
; #pragma unroll
;         for (int k2 = 0; k2 < 2; ++k2) { const int ks = 2 + k2; ga[k2][0] = ld8(Ab + 16 * ks); ga[k2][1] = ld8(Ab + 32 * LS + 16 * ks); gb[k2][0] = ld8(Bb + 16 * ks); gb[k2][1] = ld8(Bb + 32 * LS + 16 * ks); }
; #pragma unroll
;         for (int k2 = 0; k2 < 2; ++k2) {
;             acc[0][0] = MFMA(ga[k2][0], gb[k2][0], acc[0][0]); acc[0][1] = MFMA(ga[k2][0], gb[k2][1], acc[0][1]);
;             acc[1][0] = MFMA(ga[k2][1], gb[k2][0], acc[1][0]); acc[1][1] = MFMA(ga[k2][1], gb[k2][1], acc[1][1]);
;         }
;         if (kt + 1 < nk) sstore(stset, buf ^ 1, kt + 1);
; #pragma unroll
;         for (int i = 0; i < 8; ++i) { __builtin_amdgcn_sched_group_barrier(0x008, 1, 0); __builtin_amdgcn_sched_group_barrier(0x100, 1, 0); }
; #pragma unroll
;         for (int i = 0; i < 8; ++i) { __builtin_amdgcn_sched_group_barrier(0x008, 1, 0); __builtin_amdgcn_sched_group_barrier(0x200, 1, 0); }
;         __builtin_amdgcn_sched_barrier(0);
;         __syncthreads();
	global_load_dwordx4 v[140:143], v[160:161], off offset:1280
	global_load_dwordx4 v[132:135], v[0:1], off offset:1280
	global_load_dwordx4 v[120:123], v[162:163], off offset:1280
	global_load_dwordx4 v[112:115], v[152:153], off offset:1280
	global_load_dwordx4 v[96:99], v[164:165], off offset:1280
	global_load_dwordx4 v[88:91], v[154:155], off offset:1280
	global_load_dwordx4 v[80:83], v[166:167], off offset:1280
	global_load_dwordx4 v[72:75], v[156:157], off offset:1280
	ds_read_b128 v[100:103], v201
	ds_read_b128 v[108:111], v201 offset:32
	ds_read_b128 v[124:127], v201 offset:4608
	ds_read_b128 v[144:147], v201 offset:4640
	ds_read_b128 v[174:177], v200 offset:36864
	ds_read_b128 v[178:181], v200 offset:36896
	ds_read_b128 v[206:209], v200 offset:41472
	ds_read_b128 v[210:213], v200 offset:41504
	s_waitcnt lgkmcnt(3)
	v_mfma_f32_32x32x16_bf16 v[52:67], v[100:103], v[174:177], v[52:67]
	s_waitcnt lgkmcnt(1)
	v_mfma_f32_32x32x16_bf16 v[36:51], v[100:103], v[206:209], v[36:51]
	v_mfma_f32_32x32x16_bf16 v[4:19], v[124:127], v[206:209], v[4:19]
	s_waitcnt lgkmcnt(0)
	v_mfma_f32_32x32x16_bf16 v[36:51], v[108:111], v[210:213], v[36:51]
	v_mfma_f32_32x32x16_bf16 v[4:19], v[144:147], v[210:213], v[4:19]
	ds_read_b128 v[210:213], v200 offset:41568
	ds_read_b128 v[100:103], v201 offset:4672
	v_mfma_f32_32x32x16_bf16 v[20:35], v[124:127], v[174:177], v[20:35]
	ds_read_b128 v[174:177], v201 offset:4704
	ds_read_b128 v[124:127], v201 offset:64
	v_mfma_f32_32x32x16_bf16 v[52:67], v[108:111], v[178:181], v[52:67]
	ds_read_b128 v[206:209], v200 offset:36960
	ds_read_b128 v[108:111], v200 offset:41536
	v_mfma_f32_32x32x16_bf16 v[20:35], v[144:147], v[178:181], v[20:35]
	ds_read_b128 v[178:181], v200 offset:36928
	ds_read_b128 v[144:147], v201 offset:96
	s_waitcnt lgkmcnt(1)
	v_mfma_f32_32x32x16_bf16 v[52:67], v[124:127], v[178:181], v[52:67]
	s_waitcnt vmcnt(15)
	ds_write_b128 v198, v[136:139] offset:18432
	v_mfma_f32_32x32x16_bf16 v[36:51], v[124:127], v[108:111], v[36:51]
	s_waitcnt vmcnt(14)
	ds_write_b128 v198, v[128:131] offset:55296
	v_mfma_f32_32x32x16_bf16 v[20:35], v[100:103], v[178:181], v[20:35]
	s_waitcnt vmcnt(13)
	ds_write_b128 v196, v[116:119] offset:18432
	v_mfma_f32_32x32x16_bf16 v[4:19], v[100:103], v[108:111], v[4:19]
	s_waitcnt vmcnt(12)
	ds_write_b128 v196, v[104:107] offset:55296
	s_waitcnt lgkmcnt(4)
	v_mfma_f32_32x32x16_bf16 v[52:67], v[144:147], v[206:209], v[52:67]
	s_waitcnt vmcnt(11)
	ds_write_b128 v194, v[92:95] offset:18432
	v_mfma_f32_32x32x16_bf16 v[36:51], v[144:147], v[210:213], v[36:51]
	s_waitcnt vmcnt(10)
	ds_write_b128 v194, v[84:87] offset:55296
	v_mfma_f32_32x32x16_bf16 v[20:35], v[174:177], v[206:209], v[20:35]
	s_waitcnt vmcnt(9)
	ds_write_b128 v2, v[76:79] offset:18432
	v_mfma_f32_32x32x16_bf16 v[4:19], v[174:177], v[210:213], v[4:19]
	s_waitcnt vmcnt(8)
	ds_write_b128 v2, v[68:71] offset:55296
	s_waitcnt lgkmcnt(0)
	s_barrier
	global_load_dwordx4 v[124:127], v[160:161], off offset:1408
	global_load_dwordx4 v[116:119], v[0:1], off offset:1408
	global_load_dwordx4 v[108:111], v[162:163], off offset:1408
	global_load_dwordx4 v[100:103], v[152:153], off offset:1408
	global_load_dwordx4 v[92:95], v[164:165], off offset:1408
	global_load_dwordx4 v[84:87], v[154:155], off offset:1408
	global_load_dwordx4 v[76:79], v[166:167], off offset:1408
	global_load_dwordx4 v[68:71], v[156:157], off offset:1408
	ds_read_b128 v[104:107], v192
	ds_read_b128 v[128:131], v192 offset:32
	ds_read_b128 v[136:139], v192 offset:4608
	ds_read_b128 v[144:147], v192 offset:4640
	ds_read_b128 v[160:163], v191 offset:36864
	ds_read_b128 v[164:167], v191 offset:36896
	ds_read_b128 v[174:177], v191 offset:41472
	ds_read_b128 v[178:181], v191 offset:41504
	s_waitcnt lgkmcnt(3)
	v_mfma_f32_32x32x16_bf16 v[52:67], v[104:107], v[160:163], v[52:67]
	s_waitcnt lgkmcnt(1)
	v_mfma_f32_32x32x16_bf16 v[36:51], v[104:107], v[174:177], v[36:51]
	v_mfma_f32_32x32x16_bf16 v[4:19], v[136:139], v[174:177], v[4:19]
	s_waitcnt lgkmcnt(0)
	v_mfma_f32_32x32x16_bf16 v[36:51], v[128:131], v[178:181], v[36:51]
	v_mfma_f32_32x32x16_bf16 v[4:19], v[144:147], v[178:181], v[4:19]
	ds_read_b128 v[178:181], v191 offset:41568
	ds_read_b128 v[104:107], v192 offset:4672
	v_mfma_f32_32x32x16_bf16 v[20:35], v[136:139], v[160:163], v[20:35]
	ds_read_b128 v[160:163], v192 offset:4704
	ds_read_b128 v[136:139], v192 offset:64
	v_mfma_f32_32x32x16_bf16 v[52:67], v[128:131], v[164:167], v[52:67]
	ds_read_b128 v[174:177], v191 offset:36960
	ds_read_b128 v[128:131], v191 offset:41536
	v_mfma_f32_32x32x16_bf16 v[20:35], v[144:147], v[164:167], v[20:35]
	ds_read_b128 v[164:167], v191 offset:36928
	ds_read_b128 v[144:147], v192 offset:96
	s_waitcnt lgkmcnt(1)
	v_mfma_f32_32x32x16_bf16 v[52:67], v[136:139], v[164:167], v[52:67]
	s_waitcnt vmcnt(15)
	ds_write_b128 v198, v[140:143]
	v_mfma_f32_32x32x16_bf16 v[36:51], v[136:139], v[128:131], v[36:51]
	s_waitcnt vmcnt(14)
	ds_write_b128 v198, v[132:135] offset:36864
	v_mfma_f32_32x32x16_bf16 v[20:35], v[104:107], v[164:167], v[20:35]
	s_waitcnt vmcnt(13)
	ds_write_b128 v196, v[120:123]
	v_mfma_f32_32x32x16_bf16 v[4:19], v[104:107], v[128:131], v[4:19]
	s_waitcnt vmcnt(12)
	ds_write_b128 v196, v[112:115] offset:36864
	s_waitcnt lgkmcnt(4)
	v_mfma_f32_32x32x16_bf16 v[52:67], v[144:147], v[174:177], v[52:67]
	s_waitcnt vmcnt(11)
	ds_write_b128 v194, v[96:99]
	v_mfma_f32_32x32x16_bf16 v[36:51], v[144:147], v[178:181], v[36:51]
	s_waitcnt vmcnt(10)
	ds_write_b128 v194, v[88:91] offset:36864
	v_mfma_f32_32x32x16_bf16 v[20:35], v[160:163], v[174:177], v[20:35]
	s_waitcnt vmcnt(9)
	ds_write_b128 v2, v[80:83]
	v_mfma_f32_32x32x16_bf16 v[4:19], v[160:163], v[178:181], v[4:19]
	s_waitcnt vmcnt(8)
	ds_write_b128 v2, v[72:75] offset:36864
	v_mad_i64_i32 v[96:97], s[40:41], v202, s43, v[158:159]
	v_mad_i64_i32 v[98:99], s[40:41], v205, s43, v[158:159]
	v_mad_i64_i32 v[112:113], s[40:41], v204, s43, v[158:159]
	v_mad_i64_i32 v[132:133], s[40:41], v203, s43, v[158:159]
	s_waitcnt lgkmcnt(0)
	s_barrier
; template <class Epi, class ColV>
; DI void gemm_tile(const bf16_t* __restrict__ A, int lda, const bf16_t* __restrict__ Bt, int ldb, int K, int m0, int n0, unsigned char* smem, Epi epi, ColV colv, const bf16_t* __restrict__ HYT = nullptr) {
;     ...
;             if (HYT && kt >= 12) r[i] = *(const u32x4*)(HYT + (size_t)((kt - 12) * 64 + (id >> 4)) * NT + m0 + (id & 15) * 8);
;     ...
;             if (HYT && kt >= 12) { const int kk = id >> 4, rr = (id & 15) * 8; bf16_t* d = As + (buf * 128 + rr) * LS + kk; const bf16x8 v = __builtin_bit_cast(bf16x8, r[i]);
; #pragma unroll
;                 for (int e = 0; e < 8; ++e) d[e * LS] = (bf16_t)v[e]; }
;             else *(u32x4*)(As + (buf * 128 + row) * LS + kc * 8) = r[i];
;             *(u32x4*)(Bs + (buf * 128 + row) * LS + kc * 8) = r[4 + i]; }
;     ...
;     auto step = [&](int kt, u32x4 (&ldset)[8], const u32x4 (&stset)[8]) {
;         const int buf = kt & 1;
;         if (kt + 2 < nk) gload(ldset, kt + 2);
;         const bf16_t* Ab = As + (buf * 128 + 64 * wr + li) * LS + 8 * lh;
;         const bf16_t* Bb = Bs + (buf * 128 + 64 * wc + li) * LS + 8 * lh;
;         bf16x8 fa[2][2], fb[2][2], ga[2][2], gb[2][2];
; #pragma unroll
;         for (int k2 = 0; k2 < 2; ++k2) { fa[k2][0] = ld8(Ab + 16 * k2); fa[k2][1] = ld8(Ab + 32 * LS + 16 * k2); fb[k2][0] = ld8(Bb + 16 * k2); fb[k2][1] = ld8(Bb + 32 * LS + 16 * k2); }
;         __builtin_amdgcn_sched_barrier(0);
; #pragma unroll
;         for (int k2 = 0; k2 < 2; ++k2) {
;             acc[0][0] = MFMA(fa[k2][0], fb[k2][0], acc[0][0]); acc[0][1] = MFMA(fa[k2][0], fb[k2][1], acc[0][1]);
;             acc[1][0] = MFMA(fa[k2][1], fb[k2][0], acc[1][0]); acc[1][1] = MFMA(fa[k2][1], fb[k2][1], acc[1][1]);
;         }
; #pragma unroll
;         for (int k2 = 0; k2 < 2; ++k2) { const int ks = 2 + k2; ga[k2][0] = ld8(Ab + 16 * ks); ga[k2][1] = ld8(Ab + 32 * LS + 16 * ks); gb[k2][0] = ld8(Bb + 16 * ks); gb[k2][1] = ld8(Bb + 32 * LS + 16 * ks); }
; #pragma unroll
;         for (int k2 = 0; k2 < 2; ++k2) {
;             acc[0][0] = MFMA(ga[k2][0], gb[k2][0], acc[0][0]); acc[0][1] = MFMA(ga[k2][0], gb[k2][1], acc[0][1]);
;             acc[1][0] = MFMA(ga[k2][1], gb[k2][0], acc[1][0]); acc[1][1] = MFMA(ga[k2][1], gb[k2][1], acc[1][1]);
;         }
;         if (kt + 1 < nk) sstore(stset, buf ^ 1, kt + 1);
; #pragma unroll
	global_load_dwordx4 v[104:107], v[0:1], off offset:1536
	global_load_dwordx4 v[88:91], v[152:153], off offset:1536
	global_load_dwordx4 v[80:83], v[154:155], off offset:1536
	global_load_dwordx4 v[72:75], v[156:157], off offset:1536
	global_load_dwordx4 v[128:131], v[96:97], off
	global_load_dwordx4 v[120:123], v[98:99], off offset:16
	ds_read_b128 v[136:139], v201 offset:32
	global_load_dwordx4 v[112:115], v[112:113], off offset:32
	ds_read_b128 v[140:143], v201 offset:4608
	global_load_dwordx4 v[96:99], v[132:133], off offset:48
	ds_read_b128 v[132:135], v201
	ds_read_b128 v[144:147], v201 offset:4640
	ds_read_b128 v[160:163], v200 offset:36864
	ds_read_b128 v[164:167], v200 offset:36896
	ds_read_b128 v[174:177], v200 offset:41472
	ds_read_b128 v[178:181], v200 offset:41504
	s_waitcnt lgkmcnt(3)
	v_mfma_f32_32x32x16_bf16 v[52:67], v[132:135], v[160:163], v[52:67]
	s_waitcnt lgkmcnt(1)
	v_mfma_f32_32x32x16_bf16 v[36:51], v[132:135], v[174:177], v[36:51]
	v_mfma_f32_32x32x16_bf16 v[4:19], v[140:143], v[174:177], v[4:19]
	s_waitcnt lgkmcnt(0)
	v_mfma_f32_32x32x16_bf16 v[36:51], v[136:139], v[178:181], v[36:51]
	v_mfma_f32_32x32x16_bf16 v[4:19], v[144:147], v[178:181], v[4:19]
	ds_read_b128 v[178:181], v200 offset:41568
	ds_read_b128 v[132:135], v201 offset:4672
	v_mfma_f32_32x32x16_bf16 v[20:35], v[140:143], v[160:163], v[20:35]
	ds_read_b128 v[160:163], v201 offset:4704
	ds_read_b128 v[140:143], v201 offset:64
	v_mfma_f32_32x32x16_bf16 v[52:67], v[136:139], v[164:167], v[52:67]
	ds_read_b128 v[174:177], v200 offset:36960
	ds_read_b128 v[136:139], v200 offset:41536
	v_mfma_f32_32x32x16_bf16 v[20:35], v[144:147], v[164:167], v[20:35]
	ds_read_b128 v[164:167], v200 offset:36928
	ds_read_b128 v[144:147], v201 offset:96
	s_waitcnt lgkmcnt(1)
	v_mfma_f32_32x32x16_bf16 v[52:67], v[140:143], v[164:167], v[52:67]
	s_waitcnt vmcnt(15)
	ds_write_b128 v198, v[124:127] offset:18432
	v_mfma_f32_32x32x16_bf16 v[36:51], v[140:143], v[136:139], v[36:51]
	s_waitcnt vmcnt(14)
	ds_write_b128 v198, v[116:119] offset:55296
	v_mfma_f32_32x32x16_bf16 v[20:35], v[132:135], v[164:167], v[20:35]
	s_waitcnt vmcnt(13)
	ds_write_b128 v196, v[108:111] offset:18432
	v_mfma_f32_32x32x16_bf16 v[4:19], v[132:135], v[136:139], v[4:19]
	s_waitcnt vmcnt(12)
	ds_write_b128 v196, v[100:103] offset:55296
	s_waitcnt lgkmcnt(4)
	v_mfma_f32_32x32x16_bf16 v[52:67], v[144:147], v[174:177], v[52:67]
	s_waitcnt vmcnt(11)
	ds_write_b128 v194, v[92:95] offset:18432
	v_mfma_f32_32x32x16_bf16 v[36:51], v[144:147], v[178:181], v[36:51]
	s_waitcnt vmcnt(10)
	ds_write_b128 v194, v[84:87] offset:55296
	v_mfma_f32_32x32x16_bf16 v[20:35], v[160:163], v[174:177], v[20:35]
	s_waitcnt vmcnt(9)
	ds_write_b128 v2, v[76:79] offset:18432
	v_mfma_f32_32x32x16_bf16 v[4:19], v[160:163], v[178:181], v[4:19]
	s_waitcnt vmcnt(8)
	ds_write_b128 v2, v[68:71] offset:55296
	v_add_u32_e32 v68, 64, v202
	v_mad_i64_i32 v[92:93], s[40:41], v68, s43, v[158:159]
	v_add_u32_e32 v68, 64, v205
	v_mad_i64_i32 v[94:95], s[40:41], v68, s43, v[158:159]
	v_add_u32_e32 v68, 64, v204
	v_mad_i64_i32 v[108:109], s[40:41], v68, s43, v[158:159]
	v_add_u32_e32 v68, 64, v203
	v_mad_i64_i32 v[132:133], s[40:41], v68, s43, v[158:159]
	s_waitcnt lgkmcnt(0)
	s_barrier
	global_load_dwordx4 v[100:103], v[0:1], off offset:1664
	global_load_dwordx4 v[84:87], v[152:153], off offset:1664
	global_load_dwordx4 v[76:79], v[154:155], off offset:1664
	global_load_dwordx4 v[68:71], v[156:157], off offset:1664
	global_load_dwordx4 v[124:127], v[92:93], off
	global_load_dwordx4 v[116:119], v[94:95], off offset:16
	ds_read_b128 v[136:139], v192 offset:32
	global_load_dwordx4 v[108:111], v[108:109], off offset:32
	ds_read_b128 v[140:143], v192 offset:4608
	global_load_dwordx4 v[92:95], v[132:133], off offset:48
	ds_read_b128 v[132:135], v192
	ds_read_b128 v[144:147], v192 offset:4640
	ds_read_b128 v[160:163], v191 offset:36864
	ds_read_b128 v[164:167], v191 offset:36896
	ds_read_b128 v[174:177], v191 offset:41472
	ds_read_b128 v[178:181], v191 offset:41504
	s_waitcnt lgkmcnt(3)
	v_mfma_f32_32x32x16_bf16 v[52:67], v[132:135], v[160:163], v[52:67]
	s_waitcnt lgkmcnt(1)
	v_mfma_f32_32x32x16_bf16 v[36:51], v[132:135], v[174:177], v[36:51]
	v_mfma_f32_32x32x16_bf16 v[4:19], v[140:143], v[174:177], v[4:19]
	s_waitcnt lgkmcnt(0)
	v_mfma_f32_32x32x16_bf16 v[36:51], v[136:139], v[178:181], v[36:51]
	v_mfma_f32_32x32x16_bf16 v[4:19], v[144:147], v[178:181], v[4:19]
	ds_read_b128 v[178:181], v191 offset:41568
	ds_read_b128 v[132:135], v192 offset:4672
	v_mfma_f32_32x32x16_bf16 v[20:35], v[140:143], v[160:163], v[20:35]
	ds_read_b128 v[160:163], v192 offset:4704
	ds_read_b128 v[140:143], v192 offset:64
	v_mfma_f32_32x32x16_bf16 v[52:67], v[136:139], v[164:167], v[52:67]
	ds_read_b128 v[174:177], v191 offset:36960
	ds_read_b128 v[136:139], v191 offset:41536
	v_mfma_f32_32x32x16_bf16 v[20:35], v[144:147], v[164:167], v[20:35]
	ds_read_b128 v[164:167], v191 offset:36928
	ds_read_b128 v[144:147], v192 offset:96
	s_waitcnt lgkmcnt(1)
	v_mfma_f32_32x32x16_bf16 v[52:67], v[140:143], v[164:167], v[52:67]
	s_waitcnt vmcnt(11)
	ds_write_b16 v199, v128
	v_mfma_f32_32x32x16_bf16 v[36:51], v[140:143], v[136:139], v[36:51]
	ds_write_b16_d16_hi v199, v128 offset:144
	v_mfma_f32_32x32x16_bf16 v[20:35], v[132:135], v[164:167], v[20:35]
	ds_write_b16 v199, v129 offset:288
	v_mfma_f32_32x32x16_bf16 v[4:19], v[132:135], v[136:139], v[4:19]
	ds_write_b16_d16_hi v199, v129 offset:432
	s_waitcnt lgkmcnt(4)
; template <class Epi, class ColV>
; DI void gemm_tile(const bf16_t* __restrict__ A, int lda, const bf16_t* __restrict__ Bt, int ldb, int K, int m0, int n0, unsigned char* smem, Epi epi, ColV colv, const bf16_t* __restrict__ HYT = nullptr) {
;     ...
;             if (HYT && kt >= 12) { const int kk = id >> 4, rr = (id & 15) * 8; bf16_t* d = As + (buf * 128 + rr) * LS + kk; const bf16x8 v = __builtin_bit_cast(bf16x8, r[i]);
; #pragma unroll
;                 for (int e = 0; e < 8; ++e) d[e * LS] = (bf16_t)v[e]; }
;             else *(u32x4*)(As + (buf * 128 + row) * LS + kc * 8) = r[i];
;             *(u32x4*)(Bs + (buf * 128 + row) * LS + kc * 8) = r[4 + i]; }
;     ...
;     auto step = [&](int kt, u32x4 (&ldset)[8], const u32x4 (&stset)[8]) {
;         const int buf = kt & 1;
;         if (kt + 2 < nk) gload(ldset, kt + 2);
;         const bf16_t* Ab = As + (buf * 128 + 64 * wr + li) * LS + 8 * lh;
;         const bf16_t* Bb = Bs + (buf * 128 + 64 * wc + li) * LS + 8 * lh;
;         bf16x8 fa[2][2], fb[2][2], ga[2][2], gb[2][2];
; #pragma unroll
;         for (int k2 = 0; k2 < 2; ++k2) { fa[k2][0] = ld8(Ab + 16 * k2); fa[k2][1] = ld8(Ab + 32 * LS + 16 * k2); fb[k2][0] = ld8(Bb + 16 * k2); fb[k2][1] = ld8(Bb + 32 * LS + 16 * k2); }
;         __builtin_amdgcn_sched_barrier(0);
; #pragma unroll
;         for (int k2 = 0; k2 < 2; ++k2) {
;             acc[0][0] = MFMA(fa[k2][0], fb[k2][0], acc[0][0]); acc[0][1] = MFMA(fa[k2][0], fb[k2][1], acc[0][1]);
;             acc[1][0] = MFMA(fa[k2][1], fb[k2][0], acc[1][0]); acc[1][1] = MFMA(fa[k2][1], fb[k2][1], acc[1][1]);
;         }
; #pragma unroll
;         for (int k2 = 0; k2 < 2; ++k2) { const int ks = 2 + k2; ga[k2][0] = ld8(Ab + 16 * ks); ga[k2][1] = ld8(Ab + 32 * LS + 16 * ks); gb[k2][0] = ld8(Bb + 16 * ks); gb[k2][1] = ld8(Bb + 32 * LS + 16 * ks); }
; #pragma unroll
;         for (int k2 = 0; k2 < 2; ++k2) {
;             acc[0][0] = MFMA(ga[k2][0], gb[k2][0], acc[0][0]); acc[0][1] = MFMA(ga[k2][0], gb[k2][1], acc[0][1]);
;             acc[1][0] = MFMA(ga[k2][1], gb[k2][0], acc[1][0]); acc[1][1] = MFMA(ga[k2][1], gb[k2][1], acc[1][1]);
;         }
;         if (kt + 1 < nk) sstore(stset, buf ^ 1, kt + 1);
; #pragma unroll
;         for (int i = 0; i < 8; ++i) { __builtin_amdgcn_sched_group_barrier(0x008, 1, 0); __builtin_amdgcn_sched_group_barrier(0x100, 1, 0); }
; #pragma unroll
	v_mfma_f32_32x32x16_bf16 v[52:67], v[144:147], v[174:177], v[52:67]
	ds_write_b16 v199, v130 offset:576
	v_mfma_f32_32x32x16_bf16 v[36:51], v[144:147], v[178:181], v[36:51]
	ds_write_b16_d16_hi v199, v130 offset:720
	v_mfma_f32_32x32x16_bf16 v[20:35], v[160:163], v[174:177], v[20:35]
	ds_write_b16 v199, v131 offset:864
	v_mfma_f32_32x32x16_bf16 v[4:19], v[160:163], v[178:181], v[4:19]
	ds_write_b16_d16_hi v199, v131 offset:1008
	ds_write_b128 v198, v[104:107] offset:36864
	s_waitcnt vmcnt(10)
	ds_write_b16 v197, v120 offset:1152
	ds_write_b16_d16_hi v197, v120 offset:1296
	ds_write_b16 v197, v121 offset:1440
	ds_write_b16_d16_hi v197, v121 offset:1584
	ds_write_b16 v197, v122 offset:1728
	ds_write_b16_d16_hi v197, v122 offset:1872
	ds_write_b16 v197, v123 offset:2016
	ds_write_b16_d16_hi v197, v123 offset:2160
	ds_write_b128 v196, v[88:91] offset:36864
	s_waitcnt vmcnt(9)
	ds_write_b16 v195, v112 offset:2304
	ds_write_b16_d16_hi v195, v112 offset:2448
	ds_write_b16 v195, v113 offset:2592
	ds_write_b16_d16_hi v195, v113 offset:2736
	ds_write_b16 v195, v114 offset:2880
	ds_write_b16_d16_hi v195, v114 offset:3024
	ds_write_b16 v195, v115 offset:3168
	ds_write_b16_d16_hi v195, v115 offset:3312
	ds_write_b128 v194, v[80:83] offset:36864
	s_waitcnt vmcnt(8)
	ds_write_b16 v193, v96 offset:3456
	ds_write_b16_d16_hi v193, v96 offset:3600
	ds_write_b16 v193, v97 offset:3744
	ds_write_b16_d16_hi v193, v97 offset:3888
	ds_write_b16 v193, v98 offset:4032
	ds_write_b16_d16_hi v193, v98 offset:4176
	ds_write_b16 v193, v99 offset:4320
	ds_write_b16_d16_hi v193, v99 offset:4464
	ds_write_b128 v2, v[72:75] offset:36864
	v_add_u32_e32 v72, 0x80, v202
	v_mad_i64_i32 v[96:97], s[40:41], v72, s43, v[158:159]
	v_add_u32_e32 v72, 0x80, v205
	v_mad_i64_i32 v[98:99], s[40:41], v72, s43, v[158:159]
	v_add_u32_e32 v72, 0x80, v204
	v_mad_i64_i32 v[112:113], s[40:41], v72, s43, v[158:159]
	v_add_u32_e32 v72, 0x80, v203
	v_mad_i64_i32 v[132:133], s[40:41], v72, s43, v[158:159]
	s_waitcnt lgkmcnt(0)
	s_barrier
	global_load_dwordx4 v[104:107], v[0:1], off offset:1792
	global_load_dwordx4 v[88:91], v[152:153], off offset:1792
	global_load_dwordx4 v[80:83], v[154:155], off offset:1792
	global_load_dwordx4 v[72:75], v[156:157], off offset:1792
	global_load_dwordx4 v[128:131], v[96:97], off
	global_load_dwordx4 v[120:123], v[98:99], off offset:16
	ds_read_b128 v[136:139], v201 offset:32
	global_load_dwordx4 v[112:115], v[112:113], off offset:32
	ds_read_b128 v[140:143], v201 offset:4608
	global_load_dwordx4 v[96:99], v[132:133], off offset:48
	ds_read_b128 v[132:135], v201
	ds_read_b128 v[144:147], v201 offset:4640
	ds_read_b128 v[160:163], v200 offset:36864
	ds_read_b128 v[164:167], v200 offset:36896
	ds_read_b128 v[174:177], v200 offset:41472
	ds_read_b128 v[178:181], v200 offset:41504
	s_waitcnt lgkmcnt(3)
	v_mfma_f32_32x32x16_bf16 v[52:67], v[132:135], v[160:163], v[52:67]
	s_waitcnt lgkmcnt(1)
	v_mfma_f32_32x32x16_bf16 v[36:51], v[132:135], v[174:177], v[36:51]
	v_mfma_f32_32x32x16_bf16 v[4:19], v[140:143], v[174:177], v[4:19]
	s_waitcnt lgkmcnt(0)
	v_mfma_f32_32x32x16_bf16 v[36:51], v[136:139], v[178:181], v[36:51]
	v_mfma_f32_32x32x16_bf16 v[4:19], v[144:147], v[178:181], v[4:19]
	ds_read_b128 v[178:181], v200 offset:41568
	ds_read_b128 v[132:135], v201 offset:4672
	v_mfma_f32_32x32x16_bf16 v[20:35], v[140:143], v[160:163], v[20:35]
	ds_read_b128 v[160:163], v201 offset:4704
	ds_read_b128 v[140:143], v201 offset:64
	v_mfma_f32_32x32x16_bf16 v[52:67], v[136:139], v[164:167], v[52:67]
	ds_read_b128 v[174:177], v200 offset:36960
	ds_read_b128 v[136:139], v200 offset:41536
	v_mfma_f32_32x32x16_bf16 v[20:35], v[144:147], v[164:167], v[20:35]
	ds_read_b128 v[164:167], v200 offset:36928
	ds_read_b128 v[144:147], v201 offset:96
	s_waitcnt lgkmcnt(1)
	v_mfma_f32_32x32x16_bf16 v[52:67], v[140:143], v[164:167], v[52:67]
	s_waitcnt vmcnt(11)
	ds_write_b16 v199, v124 offset:18432
	v_mfma_f32_32x32x16_bf16 v[36:51], v[140:143], v[136:139], v[36:51]
	ds_write_b16_d16_hi v199, v124 offset:18576
	v_mfma_f32_32x32x16_bf16 v[20:35], v[132:135], v[164:167], v[20:35]
	ds_write_b16 v199, v125 offset:18720
	v_mfma_f32_32x32x16_bf16 v[4:19], v[132:135], v[136:139], v[4:19]
	ds_write_b16_d16_hi v199, v125 offset:18864
	s_waitcnt lgkmcnt(4)
	v_mfma_f32_32x32x16_bf16 v[52:67], v[144:147], v[174:177], v[52:67]
	ds_write_b16 v199, v126 offset:19008
	v_mfma_f32_32x32x16_bf16 v[36:51], v[144:147], v[178:181], v[36:51]
	ds_write_b16_d16_hi v199, v126 offset:19152
	v_mfma_f32_32x32x16_bf16 v[20:35], v[160:163], v[174:177], v[20:35]
	ds_write_b16 v199, v127 offset:19296
	v_mfma_f32_32x32x16_bf16 v[4:19], v[160:163], v[178:181], v[4:19]
	ds_write_b16_d16_hi v199, v127 offset:19440
	ds_write_b128 v198, v[100:103] offset:55296
	s_waitcnt vmcnt(10)
	ds_write_b16 v197, v116 offset:19584
	ds_write_b16_d16_hi v197, v116 offset:19728
	ds_write_b16 v197, v117 offset:19872
	ds_write_b16_d16_hi v197, v117 offset:20016
	ds_write_b16 v197, v118 offset:20160
	ds_write_b16_d16_hi v197, v118 offset:20304
	ds_write_b16 v197, v119 offset:20448
	ds_write_b16_d16_hi v197, v119 offset:20592
	ds_write_b128 v196, v[84:87] offset:55296
	s_waitcnt vmcnt(9)
	ds_write_b16 v195, v108 offset:20736
	ds_write_b16_d16_hi v195, v108 offset:20880
	ds_write_b16 v195, v109 offset:21024
	ds_write_b16_d16_hi v195, v109 offset:21168
	ds_write_b16 v195, v110 offset:21312
	ds_write_b16_d16_hi v195, v110 offset:21456
	ds_write_b16 v195, v111 offset:21600
	ds_write_b16_d16_hi v195, v111 offset:21744
	ds_write_b128 v194, v[76:79] offset:55296
	s_waitcnt vmcnt(8)
	ds_write_b16 v193, v92 offset:21888
	ds_write_b16_d16_hi v193, v92 offset:22032
	ds_write_b16 v193, v93 offset:22176
	ds_write_b16_d16_hi v193, v93 offset:22320
	ds_write_b16 v193, v94 offset:22464
	ds_write_b16_d16_hi v193, v94 offset:22608
	ds_write_b16 v193, v95 offset:22752
	ds_write_b16_d16_hi v193, v95 offset:22896
	ds_write_b128 v2, v[68:71] offset:55296
	v_add_u32_e32 v68, 0xc0, v202
	v_mad_i64_i32 v[92:93], s[40:41], v68, s43, v[158:159]
	v_add_u32_e32 v68, 0xc0, v205
	s_waitcnt lgkmcnt(0)
	s_barrier
; template <class Epi, class ColV>
; DI void gemm_tile(const bf16_t* __restrict__ A, int lda, const bf16_t* __restrict__ Bt, int ldb, int K, int m0, int n0, unsigned char* smem, Epi epi, ColV colv, const bf16_t* __restrict__ HYT = nullptr) {
;     ...
;             if (HYT && kt >= 12) r[i] = *(const u32x4*)(HYT + (size_t)((kt - 12) * 64 + (id >> 4)) * NT + m0 + (id & 15) * 8);
;     ...
;             if (HYT && kt >= 12) { const int kk = id >> 4, rr = (id & 15) * 8; bf16_t* d = As + (buf * 128 + rr) * LS + kk; const bf16x8 v = __builtin_bit_cast(bf16x8, r[i]);
; #pragma unroll
;                 for (int e = 0; e < 8; ++e) d[e * LS] = (bf16_t)v[e]; }
;             else *(u32x4*)(As + (buf * 128 + row) * LS + kc * 8) = r[i];
;             *(u32x4*)(Bs + (buf * 128 + row) * LS + kc * 8) = r[4 + i]; }
;     ...
;     auto step = [&](int kt, u32x4 (&ldset)[8], const u32x4 (&stset)[8]) {
;         const int buf = kt & 1;
;         if (kt + 2 < nk) gload(ldset, kt + 2);
;         const bf16_t* Ab = As + (buf * 128 + 64 * wr + li) * LS + 8 * lh;
;         const bf16_t* Bb = Bs + (buf * 128 + 64 * wc + li) * LS + 8 * lh;
;         bf16x8 fa[2][2], fb[2][2], ga[2][2], gb[2][2];
; #pragma unroll
;         for (int k2 = 0; k2 < 2; ++k2) { fa[k2][0] = ld8(Ab + 16 * k2); fa[k2][1] = ld8(Ab + 32 * LS + 16 * k2); fb[k2][0] = ld8(Bb + 16 * k2); fb[k2][1] = ld8(Bb + 32 * LS + 16 * k2); }
;         __builtin_amdgcn_sched_barrier(0);
; #pragma unroll
;         for (int k2 = 0; k2 < 2; ++k2) {
;             acc[0][0] = MFMA(fa[k2][0], fb[k2][0], acc[0][0]); acc[0][1] = MFMA(fa[k2][0], fb[k2][1], acc[0][1]);
;             acc[1][0] = MFMA(fa[k2][1], fb[k2][0], acc[1][0]); acc[1][1] = MFMA(fa[k2][1], fb[k2][1], acc[1][1]);
;         }
; #pragma unroll
;         for (int k2 = 0; k2 < 2; ++k2) { const int ks = 2 + k2; ga[k2][0] = ld8(Ab + 16 * ks); ga[k2][1] = ld8(Ab + 32 * LS + 16 * ks); gb[k2][0] = ld8(Bb + 16 * ks); gb[k2][1] = ld8(Bb + 32 * LS + 16 * ks); }
; #pragma unroll
;         for (int k2 = 0; k2 < 2; ++k2) {
;             acc[0][0] = MFMA(ga[k2][0], gb[k2][0], acc[0][0]); acc[0][1] = MFMA(ga[k2][0], gb[k2][1], acc[0][1]);
;             acc[1][0] = MFMA(ga[k2][1], gb[k2][0], acc[1][0]); acc[1][1] = MFMA(ga[k2][1], gb[k2][1], acc[1][1]);
;         }
;         if (kt + 1 < nk) sstore(stset, buf ^ 1, kt + 1);
; #pragma unroll
	v_mad_i64_i32 v[94:95], s[40:41], v68, s43, v[158:159]
	global_load_dwordx4 v[100:103], v[0:1], off offset:1920
	v_add_u32_e32 v0, 0xc0, v204
	v_add_u32_e32 v68, 0xc0, v203
	v_mad_i64_i32 v[0:1], s[40:41], v0, s43, v[158:159]
	v_mad_i64_i32 v[132:133], s[40:41], v68, s43, v[158:159]
	global_load_dwordx4 v[84:87], v[152:153], off offset:1920
	global_load_dwordx4 v[76:79], v[154:155], off offset:1920
	global_load_dwordx4 v[68:71], v[156:157], off offset:1920
	global_load_dwordx4 v[124:127], v[92:93], off
	global_load_dwordx4 v[116:119], v[94:95], off offset:16
	global_load_dwordx4 v[108:111], v[0:1], off offset:32
	ds_read_b128 v[136:139], v192 offset:32
	global_load_dwordx4 v[92:95], v[132:133], off offset:48
	ds_read_b128 v[132:135], v192
	ds_read_b128 v[140:143], v192 offset:4608
	ds_read_b128 v[144:147], v192 offset:4640
	ds_read_b128 v[152:155], v191 offset:36864
	ds_read_b128 v[156:159], v191 offset:36896
	ds_read_b128 v[160:163], v191 offset:41472
	ds_read_b128 v[164:167], v191 offset:41504
	s_waitcnt lgkmcnt(3)
	v_mfma_f32_32x32x16_bf16 v[52:67], v[132:135], v[152:155], v[52:67]
	s_waitcnt lgkmcnt(1)
	v_mfma_f32_32x32x16_bf16 v[36:51], v[132:135], v[160:163], v[36:51]
	v_mfma_f32_32x32x16_bf16 v[4:19], v[140:143], v[160:163], v[4:19]
	s_waitcnt lgkmcnt(0)
	v_mfma_f32_32x32x16_bf16 v[36:51], v[136:139], v[164:167], v[36:51]
	v_mfma_f32_32x32x16_bf16 v[4:19], v[144:147], v[164:167], v[4:19]
	ds_read_b128 v[164:167], v191 offset:41568
	ds_read_b128 v[132:135], v192 offset:4672
	v_mfma_f32_32x32x16_bf16 v[20:35], v[140:143], v[152:155], v[20:35]
	ds_read_b128 v[152:155], v192 offset:4704
	ds_read_b128 v[140:143], v192 offset:64
	v_mfma_f32_32x32x16_bf16 v[52:67], v[136:139], v[156:159], v[52:67]
	ds_read_b128 v[160:163], v191 offset:36960
	ds_read_b128 v[136:139], v191 offset:41536
	v_mfma_f32_32x32x16_bf16 v[20:35], v[144:147], v[156:159], v[20:35]
	ds_read_b128 v[156:159], v191 offset:36928
	ds_read_b128 v[144:147], v192 offset:96
	s_waitcnt lgkmcnt(1)
	v_mfma_f32_32x32x16_bf16 v[52:67], v[140:143], v[156:159], v[52:67]
	s_waitcnt vmcnt(11)
	ds_write_b16 v199, v128
	v_mfma_f32_32x32x16_bf16 v[36:51], v[140:143], v[136:139], v[36:51]
	ds_write_b16_d16_hi v199, v128 offset:144
	v_mfma_f32_32x32x16_bf16 v[20:35], v[132:135], v[156:159], v[20:35]
	ds_write_b16 v199, v129 offset:288
	v_mfma_f32_32x32x16_bf16 v[4:19], v[132:135], v[136:139], v[4:19]
	ds_write_b16_d16_hi v199, v129 offset:432
	s_waitcnt lgkmcnt(4)
	v_mfma_f32_32x32x16_bf16 v[52:67], v[144:147], v[160:163], v[52:67]
	ds_write_b16 v199, v130 offset:576
	v_mfma_f32_32x32x16_bf16 v[36:51], v[144:147], v[164:167], v[36:51]
	ds_write_b16_d16_hi v199, v130 offset:720
	v_mfma_f32_32x32x16_bf16 v[20:35], v[152:155], v[160:163], v[20:35]
	ds_write_b16 v199, v131 offset:864
	v_mfma_f32_32x32x16_bf16 v[4:19], v[152:155], v[164:167], v[4:19]
	ds_write_b16_d16_hi v199, v131 offset:1008
	ds_write_b128 v198, v[104:107] offset:36864
	s_waitcnt vmcnt(10)
	ds_write_b16 v197, v120 offset:1152
	ds_write_b16_d16_hi v197, v120 offset:1296
	ds_write_b16 v197, v121 offset:1440
	ds_write_b16_d16_hi v197, v121 offset:1584
	ds_write_b16 v197, v122 offset:1728
	ds_write_b16_d16_hi v197, v122 offset:1872
	ds_write_b16 v197, v123 offset:2016
	ds_write_b16_d16_hi v197, v123 offset:2160
	ds_write_b128 v196, v[88:91] offset:36864
	s_waitcnt vmcnt(9)
	ds_write_b16 v195, v112 offset:2304
	ds_write_b16_d16_hi v195, v112 offset:2448
	ds_write_b16 v195, v113 offset:2592
	ds_write_b16_d16_hi v195, v113 offset:2736
	ds_write_b16 v195, v114 offset:2880
	ds_write_b16_d16_hi v195, v114 offset:3024
	ds_write_b16 v195, v115 offset:3168
	ds_write_b16_d16_hi v195, v115 offset:3312
	ds_write_b128 v194, v[80:83] offset:36864
	s_waitcnt vmcnt(8)
	ds_write_b16 v193, v96 offset:3456
	ds_write_b16_d16_hi v193, v96 offset:3600
	ds_write_b16 v193, v97 offset:3744
	ds_write_b16_d16_hi v193, v97 offset:3888
	ds_write_b16 v193, v98 offset:4032
	ds_write_b16_d16_hi v193, v98 offset:4176
	ds_write_b16 v193, v99 offset:4320
	ds_write_b16_d16_hi v193, v99 offset:4464
	ds_write_b128 v2, v[72:75] offset:36864
	s_waitcnt lgkmcnt(0)
	s_barrier
	ds_read_b128 v[72:75], v201
	ds_read_b128 v[80:83], v201 offset:32
	ds_read_b128 v[88:91], v201 offset:4608
	ds_read_b128 v[96:99], v201 offset:4640
	ds_read_b128 v[104:107], v200 offset:36864
	ds_read_b128 v[112:115], v200 offset:36896
	ds_read_b128 v[120:123], v200 offset:41472
	ds_read_b128 v[128:131], v200 offset:41504
	s_waitcnt lgkmcnt(3)
	v_mfma_f32_32x32x16_bf16 v[52:67], v[72:75], v[104:107], v[52:67]
	s_waitcnt lgkmcnt(1)
	v_mfma_f32_32x32x16_bf16 v[36:51], v[72:75], v[120:123], v[36:51]
	v_mfma_f32_32x32x16_bf16 v[4:19], v[88:91], v[120:123], v[4:19]
	s_waitcnt lgkmcnt(0)
	v_mfma_f32_32x32x16_bf16 v[36:51], v[80:83], v[128:131], v[36:51]
	v_mfma_f32_32x32x16_bf16 v[4:19], v[96:99], v[128:131], v[4:19]
	ds_read_b128 v[128:131], v200 offset:41568
	ds_read_b128 v[72:75], v201 offset:4672
	v_mfma_f32_32x32x16_bf16 v[20:35], v[88:91], v[104:107], v[20:35]
	ds_read_b128 v[104:107], v201 offset:4704
	ds_read_b128 v[88:91], v201 offset:64
	v_mfma_f32_32x32x16_bf16 v[52:67], v[80:83], v[112:115], v[52:67]
	ds_read_b128 v[120:123], v200 offset:36960
	ds_read_b128 v[80:83], v200 offset:41536
	v_mfma_f32_32x32x16_bf16 v[20:35], v[96:99], v[112:115], v[20:35]
	ds_read_b128 v[112:115], v200 offset:36928
	ds_read_b128 v[96:99], v201 offset:96
	s_waitcnt lgkmcnt(1)
	v_mfma_f32_32x32x16_bf16 v[52:67], v[88:91], v[112:115], v[52:67]
	s_waitcnt vmcnt(3)
; template <class Epi, class ColV>
; DI void gemm_tile(const bf16_t* __restrict__ A, int lda, const bf16_t* __restrict__ Bt, int ldb, int K, int m0, int n0, unsigned char* smem, Epi epi, ColV colv, const bf16_t* __restrict__ HYT = nullptr) {
;     ...
;             if (HYT && kt >= 12) { const int kk = id >> 4, rr = (id & 15) * 8; bf16_t* d = As + (buf * 128 + rr) * LS + kk; const bf16x8 v = __builtin_bit_cast(bf16x8, r[i]);
; #pragma unroll
;                 for (int e = 0; e < 8; ++e) d[e * LS] = (bf16_t)v[e]; }
;             else *(u32x4*)(As + (buf * 128 + row) * LS + kc * 8) = r[i];
;             *(u32x4*)(Bs + (buf * 128 + row) * LS + kc * 8) = r[4 + i]; }
;     ...
;     for (int kt = 0; kt < nk; kt += 2) {
;         step(kt, R0, R1);
;         if (kt + 1 < nk) step(kt + 1, R1, R0);
;     }
;     const float cv0 = colv(m0, n0 + 64 * wc + li), cv1 = colv(m0, n0 + 64 * wc + 32 + li);
;     ...
;         auto gate = [&](int m0_, int c) { return MOD[(m0_ < NL ? (m0_ >> 12) : 4) * 6144 + 2048 + c]; };
;         auto epi = [&](int r, int c, float v, float ga) {
;             if (r < NL) { const size_t o = (size_t)r * 1024 + c; out[o] = (layer == 0 ? xin[o] : out[o]) + ga * v; }
;             else { const size_t o = (size_t)(r - NL) * 1024 + c; XC[o] = cin[o] + ga * v; } };
	ds_write_b16 v199, v124 offset:18432
	v_mfma_f32_32x32x16_bf16 v[36:51], v[88:91], v[80:83], v[36:51]
	ds_write_b16_d16_hi v199, v124 offset:18576
	v_mfma_f32_32x32x16_bf16 v[20:35], v[72:75], v[112:115], v[20:35]
	ds_write_b16 v199, v125 offset:18720
	v_mfma_f32_32x32x16_bf16 v[4:19], v[72:75], v[80:83], v[4:19]
	ds_write_b16_d16_hi v199, v125 offset:18864
	s_waitcnt lgkmcnt(4)
	v_mfma_f32_32x32x16_bf16 v[52:67], v[96:99], v[120:123], v[52:67]
	ds_write_b16 v199, v126 offset:19008
	v_mfma_f32_32x32x16_bf16 v[36:51], v[96:99], v[128:131], v[36:51]
	ds_write_b16_d16_hi v199, v126 offset:19152
	v_mfma_f32_32x32x16_bf16 v[20:35], v[104:107], v[120:123], v[20:35]
	ds_write_b16 v199, v127 offset:19296
	v_mfma_f32_32x32x16_bf16 v[4:19], v[104:107], v[128:131], v[4:19]
	ds_write_b16_d16_hi v199, v127 offset:19440
	ds_write_b128 v198, v[100:103] offset:55296
	s_waitcnt vmcnt(2)
	ds_write_b16 v197, v116 offset:19584
	ds_write_b16_d16_hi v197, v116 offset:19728
	ds_write_b16 v197, v117 offset:19872
	ds_write_b16_d16_hi v197, v117 offset:20016
	ds_write_b16 v197, v118 offset:20160
	ds_write_b16_d16_hi v197, v118 offset:20304
	ds_write_b16 v197, v119 offset:20448
	ds_write_b16_d16_hi v197, v119 offset:20592
	ds_write_b128 v196, v[84:87] offset:55296
	s_waitcnt vmcnt(1)
	ds_write_b16 v195, v108 offset:20736
	ds_write_b16_d16_hi v195, v108 offset:20880
	ds_write_b16 v195, v109 offset:21024
	ds_write_b16_d16_hi v195, v109 offset:21168
	ds_write_b16 v195, v110 offset:21312
	ds_write_b16_d16_hi v195, v110 offset:21456
	ds_write_b16 v195, v111 offset:21600
	ds_write_b16_d16_hi v195, v111 offset:21744
	ds_write_b128 v194, v[76:79] offset:55296
	s_waitcnt vmcnt(0)
	ds_write_b16 v193, v92 offset:21888
	ds_write_b16_d16_hi v193, v92 offset:22032
	ds_write_b16 v193, v93 offset:22176
	ds_write_b16_d16_hi v193, v93 offset:22320
	ds_write_b16 v193, v94 offset:22464
	ds_write_b16_d16_hi v193, v94 offset:22608
	ds_write_b16 v193, v95 offset:22752
	ds_write_b16_d16_hi v193, v95 offset:22896
	ds_write_b128 v2, v[68:71] offset:55296
	s_waitcnt lgkmcnt(0)
	s_barrier
	ds_read_b128 v[68:71], v192
	ds_read_b128 v[72:75], v192 offset:32
	ds_read_b128 v[76:79], v192 offset:4608
	ds_read_b128 v[80:83], v192 offset:4640
	ds_read_b128 v[84:87], v191 offset:36864
	ds_read_b128 v[88:91], v191 offset:36896
	ds_read_b128 v[92:95], v191 offset:41472
	ds_read_b128 v[96:99], v191 offset:41504
	s_waitcnt lgkmcnt(3)
	v_mfma_f32_32x32x16_bf16 v[52:67], v[68:71], v[84:87], v[52:67]
	s_waitcnt lgkmcnt(1)
	v_mfma_f32_32x32x16_bf16 v[36:51], v[68:71], v[92:95], v[36:51]
	v_mfma_f32_32x32x16_bf16 v[4:19], v[76:79], v[92:95], v[4:19]
	s_waitcnt lgkmcnt(0)
	v_mfma_f32_32x32x16_bf16 v[36:51], v[72:75], v[96:99], v[36:51]
	v_mfma_f32_32x32x16_bf16 v[4:19], v[80:83], v[96:99], v[4:19]
	ds_read_b128 v[96:99], v191 offset:41568
	ds_read_b128 v[68:71], v192 offset:4672
	v_mfma_f32_32x32x16_bf16 v[20:35], v[76:79], v[84:87], v[20:35]
	ds_read_b128 v[84:87], v192 offset:4704
	ds_read_b128 v[76:79], v192 offset:64
	v_mfma_f32_32x32x16_bf16 v[52:67], v[72:75], v[88:91], v[52:67]
	ds_read_b128 v[92:95], v191 offset:36960
	ds_read_b128 v[72:75], v191 offset:41536
	v_mfma_f32_32x32x16_bf16 v[20:35], v[80:83], v[88:91], v[20:35]
	ds_read_b128 v[88:91], v191 offset:36928
	ds_read_b128 v[80:83], v192 offset:96
	s_waitcnt lgkmcnt(1)
	v_mfma_f32_32x32x16_bf16 v[52:67], v[76:79], v[88:91], v[52:67]
	v_mfma_f32_32x32x16_bf16 v[36:51], v[76:79], v[72:75], v[36:51]
	v_mfma_f32_32x32x16_bf16 v[20:35], v[68:71], v[88:91], v[20:35]
	v_mfma_f32_32x32x16_bf16 v[4:19], v[68:71], v[72:75], v[4:19]
	s_waitcnt lgkmcnt(0)
	v_mfma_f32_32x32x16_bf16 v[52:67], v[80:83], v[92:95], v[52:67]
	v_mfma_f32_32x32x16_bf16 v[36:51], v[80:83], v[96:99], v[36:51]
	v_mfma_f32_32x32x16_bf16 v[20:35], v[84:87], v[92:95], v[20:35]
	v_mfma_f32_32x32x16_bf16 v[4:19], v[84:87], v[96:99], v[4:19]
	s_min_i32 s13, s12, 0x4000
	s_ashr_i32 s13, s13, 12
	s_mulk_i32 s13, 0x1800
	v_bitop3_b32 v68, v151, 31, 64 bitop3:0xe0
	v_or_b32_e32 v0, s13, v68
	v_subrev_u32_e32 v0, s38, v0
	v_add_u32_e32 v2, s36, v0
	v_add_u32_e32 v0, 0x800, v2
	v_ashrrev_i32_e32 v1, 31, v0
	v_lshl_add_u64 v[0:1], v[0:1], 2, s[46:47]
	s_barrier
	global_load_dword v108, v[0:1], off
	v_add_u32_e32 v0, 0x820, v2
	v_ashrrev_i32_e32 v1, 31, v0
	v_lshl_add_u64 v[0:1], v[0:1], 2, s[46:47]
	global_load_dword v2, v[0:1], off
	v_add_u32_e32 v0, s12, v190
	v_lshl_or_b32 v109, v148, 2, v0
	v_subrev_u32_e32 v0, s38, v68
	v_add_u32_e32 v0, s36, v0
	s_cmp_lt_i32 s12, 0x4000
	s_cselect_b32 s100, s15, s48
	s_cselect_b32 s101, s9, s49
	s_cselect_b32 s13, 0, 0x4000
	v_subrev_u32_e32 v109, s13, v109
	v_lshlrev_b32_e32 v109, 12, v109
	v_lshl_add_u32 v109, v0, 2, v109
	s_cselect_b32 s12, s24, s96
	s_cselect_b32 s13, s25, s97
	v_mov_b32_e32 v0, v109
	global_load_dword v69, v0, s[100:101]
	global_load_dword v70, v0, s[100:101] offset:128
	v_add_u32_e32 v0, 0x1000, v0
	global_load_dword v71, v0, s[100:101]
	global_load_dword v72, v0, s[100:101] offset:128
	v_add_u32_e32 v0, 0x1000, v0
	global_load_dword v73, v0, s[100:101]
	global_load_dword v74, v0, s[100:101] offset:128
	v_add_u32_e32 v0, 0x1000, v0
	global_load_dword v75, v0, s[100:101]
	global_load_dword v76, v0, s[100:101] offset:128
	v_add_u32_e32 v0, 0x5000, v0
	global_load_dword v77, v0, s[100:101]
	global_load_dword v78, v0, s[100:101] offset:128
	v_add_u32_e32 v0, 0x1000, v0
	global_load_dword v79, v0, s[100:101]
	global_load_dword v80, v0, s[100:101] offset:128
	v_add_u32_e32 v0, 0x1000, v0
	global_load_dword v81, v0, s[100:101]
	global_load_dword v82, v0, s[100:101] offset:128
	v_add_u32_e32 v0, 0x1000, v0
	global_load_dword v83, v0, s[100:101]
; DI int crow(int reg, int h) { return (reg & 3) + 8 * (reg >> 2) + 4 * h; }
; template <class Epi, class ColV>
; DI void gemm_tile(const bf16_t* __restrict__ A, int lda, const bf16_t* __restrict__ Bt, int ldb, int K, int m0, int n0, unsigned char* smem, Epi epi, ColV colv, const bf16_t* __restrict__ HYT = nullptr) {
;     ...
;     const float cv0 = colv(m0, n0 + 64 * wc + li), cv1 = colv(m0, n0 + 64 * wc + 32 + li);
; #pragma unroll
;     for (int mi = 0; mi < 2; ++mi)
; #pragma unroll
;         for (int ni = 0; ni < 2; ++ni)
; #pragma unroll
;             for (int reg = 0; reg < 16; ++reg)
;                 epi(m0 + 64 * wr + 32 * mi + crow(reg, lh), n0 + 64 * wc + 32 * ni + li, acc[mi][ni][reg], ni ? cv1 : cv0);
;     ...
;         auto epi = [&](int r, int c, float v, float ga) {
;             if (r < NL) { const size_t o = (size_t)r * 1024 + c; out[o] = (layer == 0 ? xin[o] : out[o]) + ga * v; }
;             else { const size_t o = (size_t)(r - NL) * 1024 + c; XC[o] = cin[o] + ga * v; } };
	global_load_dword v84, v0, s[100:101] offset:128
	v_add_u32_e32 v0, 0x5000, v0
	global_load_dword v85, v0, s[100:101]
	global_load_dword v86, v0, s[100:101] offset:128
	v_add_u32_e32 v0, 0x1000, v0
	global_load_dword v87, v0, s[100:101]
	global_load_dword v88, v0, s[100:101] offset:128
	v_add_u32_e32 v0, 0x1000, v0
	global_load_dword v89, v0, s[100:101]
	global_load_dword v90, v0, s[100:101] offset:128
	v_add_u32_e32 v0, 0x1000, v0
	global_load_dword v91, v0, s[100:101]
	global_load_dword v92, v0, s[100:101] offset:128
	v_add_u32_e32 v0, 0x5000, v0
	global_load_dword v93, v0, s[100:101]
	global_load_dword v94, v0, s[100:101] offset:128
	v_add_u32_e32 v0, 0x1000, v0
	global_load_dword v95, v0, s[100:101]
	global_load_dword v96, v0, s[100:101] offset:128
	v_add_u32_e32 v0, 0x1000, v0
	global_load_dword v97, v0, s[100:101]
	global_load_dword v98, v0, s[100:101] offset:128
	v_add_u32_e32 v0, 0x1000, v0
	global_load_dword v99, v0, s[100:101]
	global_load_dword v100, v0, s[100:101] offset:128
	v_add_u32_e32 v0, 0x20000, v109
	global_load_dword v101, v0, s[100:101]
	global_load_dword v102, v0, s[100:101] offset:128
	v_add_u32_e32 v0, 0x1000, v0
	global_load_dword v103, v0, s[100:101]
	global_load_dword v104, v0, s[100:101] offset:128
	v_add_u32_e32 v0, 0x1000, v0
	global_load_dword v105, v0, s[100:101]
	global_load_dword v106, v0, s[100:101] offset:128
	v_add_u32_e32 v0, 0x1000, v0
	global_load_dword v107, v0, s[100:101]
	global_load_dword v110, v0, s[100:101] offset:128
	v_add_u32_e32 v0, 0x5000, v0
	global_load_dword v111, v0, s[100:101]
	global_load_dword v112, v0, s[100:101] offset:128
	v_add_u32_e32 v0, 0x1000, v0
	global_load_dword v113, v0, s[100:101]
	global_load_dword v114, v0, s[100:101] offset:128
	v_add_u32_e32 v0, 0x1000, v0
	global_load_dword v115, v0, s[100:101]
	global_load_dword v116, v0, s[100:101] offset:128
	v_add_u32_e32 v0, 0x1000, v0
	global_load_dword v117, v0, s[100:101]
	global_load_dword v118, v0, s[100:101] offset:128
	v_add_u32_e32 v0, 0x5000, v0
	global_load_dword v119, v0, s[100:101]
	global_load_dword v120, v0, s[100:101] offset:128
	v_add_u32_e32 v0, 0x1000, v0
	global_load_dword v121, v0, s[100:101]
	global_load_dword v122, v0, s[100:101] offset:128
	v_add_u32_e32 v0, 0x1000, v0
	global_load_dword v123, v0, s[100:101]
	global_load_dword v124, v0, s[100:101] offset:128
	v_add_u32_e32 v0, 0x1000, v0
	global_load_dword v125, v0, s[100:101]
	global_load_dword v126, v0, s[100:101] offset:128
	v_add_u32_e32 v0, 0x5000, v0
	global_load_dword v127, v0, s[100:101]
	global_load_dword v128, v0, s[100:101] offset:128
	v_add_u32_e32 v0, 0x1000, v0
	global_load_dword v129, v0, s[100:101]
	global_load_dword v130, v0, s[100:101] offset:128
	v_add_u32_e32 v0, 0x1000, v0
	global_load_dword v131, v0, s[100:101]
	global_load_dword v132, v0, s[100:101] offset:128
	v_add_u32_e32 v0, 0x1000, v0
	global_load_dword v133, v0, s[100:101]
	global_load_dword v134, v0, s[100:101] offset:128
	s_waitcnt vmcnt(32)
	v_fmac_f32_e32 v69, v52, v108
	v_fmac_f32_e32 v70, v36, v2
	v_fmac_f32_e32 v71, v53, v108
	v_fmac_f32_e32 v72, v37, v2
	v_fmac_f32_e32 v73, v54, v108
	v_fmac_f32_e32 v74, v38, v2
	v_fmac_f32_e32 v75, v55, v108
	v_fmac_f32_e32 v76, v39, v2
	v_fmac_f32_e32 v77, v56, v108
	v_fmac_f32_e32 v78, v40, v2
	v_fmac_f32_e32 v79, v57, v108
	v_fmac_f32_e32 v80, v41, v2
	v_fmac_f32_e32 v81, v58, v108
	v_fmac_f32_e32 v82, v42, v2
	v_fmac_f32_e32 v83, v59, v108
	v_fmac_f32_e32 v84, v43, v2
	v_fmac_f32_e32 v85, v60, v108
	v_fmac_f32_e32 v86, v44, v2
	v_fmac_f32_e32 v87, v61, v108
	v_fmac_f32_e32 v88, v45, v2
	v_fmac_f32_e32 v89, v62, v108
	v_fmac_f32_e32 v90, v46, v2
	v_fmac_f32_e32 v91, v63, v108
	v_fmac_f32_e32 v92, v47, v2
	v_fmac_f32_e32 v93, v64, v108
	v_fmac_f32_e32 v94, v48, v2
	v_fmac_f32_e32 v95, v65, v108
	v_fmac_f32_e32 v96, v49, v2
	v_fmac_f32_e32 v97, v66, v108
	v_fmac_f32_e32 v98, v50, v2
	v_fmac_f32_e32 v99, v67, v108
	v_fmac_f32_e32 v100, v51, v2
	v_mov_b32_e32 v0, v109
	global_store_dword v0, v69, s[12:13]
	global_store_dword v0, v70, s[12:13] offset:128
	v_add_u32_e32 v0, 0x1000, v0
	global_store_dword v0, v71, s[12:13]
	global_store_dword v0, v72, s[12:13] offset:128
	v_add_u32_e32 v0, 0x1000, v0
	global_store_dword v0, v73, s[12:13]
	global_store_dword v0, v74, s[12:13] offset:128
	v_add_u32_e32 v0, 0x1000, v0
	global_store_dword v0, v75, s[12:13]
	global_store_dword v0, v76, s[12:13] offset:128
	v_add_u32_e32 v0, 0x5000, v0
	global_store_dword v0, v77, s[12:13]
	global_store_dword v0, v78, s[12:13] offset:128
	v_add_u32_e32 v0, 0x1000, v0
	global_store_dword v0, v79, s[12:13]
	global_store_dword v0, v80, s[12:13] offset:128
	v_add_u32_e32 v0, 0x1000, v0
	global_store_dword v0, v81, s[12:13]
	global_store_dword v0, v82, s[12:13] offset:128
	v_add_u32_e32 v0, 0x1000, v0
	global_store_dword v0, v83, s[12:13]
	global_store_dword v0, v84, s[12:13] offset:128
	v_add_u32_e32 v0, 0x5000, v0
	global_store_dword v0, v85, s[12:13]
	global_store_dword v0, v86, s[12:13] offset:128
	v_add_u32_e32 v0, 0x1000, v0
	global_store_dword v0, v87, s[12:13]
	global_store_dword v0, v88, s[12:13] offset:128
	v_add_u32_e32 v0, 0x1000, v0
	global_store_dword v0, v89, s[12:13]
	global_store_dword v0, v90, s[12:13] offset:128
	v_add_u32_e32 v0, 0x1000, v0
	global_store_dword v0, v91, s[12:13]
	global_store_dword v0, v92, s[12:13] offset:128
	v_add_u32_e32 v0, 0x5000, v0
	global_store_dword v0, v93, s[12:13]
	global_store_dword v0, v94, s[12:13] offset:128
	v_add_u32_e32 v0, 0x1000, v0
	global_store_dword v0, v95, s[12:13]
	global_store_dword v0, v96, s[12:13] offset:128
	v_add_u32_e32 v0, 0x1000, v0
	global_store_dword v0, v97, s[12:13]
	global_store_dword v0, v98, s[12:13] offset:128
	v_add_u32_e32 v0, 0x1000, v0
	global_store_dword v0, v99, s[12:13]
	global_store_dword v0, v100, s[12:13] offset:128
	s_waitcnt vmcnt(32)
;     ...
;         auto epi = [&](int r, int c, float v, float ga) {
;             if (r < NL) { const size_t o = (size_t)r * 1024 + c; out[o] = (layer == 0 ? xin[o] : out[o]) + ga * v; }
;             else { const size_t o = (size_t)(r - NL) * 1024 + c; XC[o] = cin[o] + ga * v; } };
	v_fmac_f32_e32 v101, v20, v108
	v_fmac_f32_e32 v102, v4, v2
	v_fmac_f32_e32 v103, v21, v108
	v_fmac_f32_e32 v104, v5, v2
	v_fmac_f32_e32 v105, v22, v108
	v_fmac_f32_e32 v106, v6, v2
	v_fmac_f32_e32 v107, v23, v108
	v_fmac_f32_e32 v110, v7, v2
	v_fmac_f32_e32 v111, v24, v108
	v_fmac_f32_e32 v112, v8, v2
	v_fmac_f32_e32 v113, v25, v108
	v_fmac_f32_e32 v114, v9, v2
	v_fmac_f32_e32 v115, v26, v108
	v_fmac_f32_e32 v116, v10, v2
	v_fmac_f32_e32 v117, v27, v108
	v_fmac_f32_e32 v118, v11, v2
	v_fmac_f32_e32 v119, v28, v108
	v_fmac_f32_e32 v120, v12, v2
	v_fmac_f32_e32 v121, v29, v108
	v_fmac_f32_e32 v122, v13, v2
	v_fmac_f32_e32 v123, v30, v108
	v_fmac_f32_e32 v124, v14, v2
	v_fmac_f32_e32 v125, v31, v108
	v_fmac_f32_e32 v126, v15, v2
	v_fmac_f32_e32 v127, v32, v108
	v_fmac_f32_e32 v128, v16, v2
	v_fmac_f32_e32 v129, v33, v108
	v_fmac_f32_e32 v130, v17, v2
	v_fmac_f32_e32 v131, v34, v108
	v_fmac_f32_e32 v132, v18, v2
	v_fmac_f32_e32 v133, v35, v108
	v_fmac_f32_e32 v134, v19, v2
	v_add_u32_e32 v0, 0x20000, v109
	global_store_dword v0, v101, s[12:13]
	global_store_dword v0, v102, s[12:13] offset:128
	v_add_u32_e32 v0, 0x1000, v0
	global_store_dword v0, v103, s[12:13]
	global_store_dword v0, v104, s[12:13] offset:128
	v_add_u32_e32 v0, 0x1000, v0
	global_store_dword v0, v105, s[12:13]
	global_store_dword v0, v106, s[12:13] offset:128
	v_add_u32_e32 v0, 0x1000, v0
	global_store_dword v0, v107, s[12:13]
	global_store_dword v0, v110, s[12:13] offset:128
	v_add_u32_e32 v0, 0x5000, v0
	global_store_dword v0, v111, s[12:13]
	global_store_dword v0, v112, s[12:13] offset:128
	v_add_u32_e32 v0, 0x1000, v0
	global_store_dword v0, v113, s[12:13]
	global_store_dword v0, v114, s[12:13] offset:128
	v_add_u32_e32 v0, 0x1000, v0
	global_store_dword v0, v115, s[12:13]
	global_store_dword v0, v116, s[12:13] offset:128
	v_add_u32_e32 v0, 0x1000, v0
	global_store_dword v0, v117, s[12:13]
	global_store_dword v0, v118, s[12:13] offset:128
	v_add_u32_e32 v0, 0x5000, v0
	global_store_dword v0, v119, s[12:13]
	global_store_dword v0, v120, s[12:13] offset:128
	v_add_u32_e32 v0, 0x1000, v0
	global_store_dword v0, v121, s[12:13]
	global_store_dword v0, v122, s[12:13] offset:128
	v_add_u32_e32 v0, 0x1000, v0
	global_store_dword v0, v123, s[12:13]
	global_store_dword v0, v124, s[12:13] offset:128
	v_add_u32_e32 v0, 0x1000, v0
	global_store_dword v0, v125, s[12:13]
	global_store_dword v0, v126, s[12:13] offset:128
	v_add_u32_e32 v0, 0x5000, v0
	global_store_dword v0, v127, s[12:13]
	global_store_dword v0, v128, s[12:13] offset:128
	v_add_u32_e32 v0, 0x1000, v0
	global_store_dword v0, v129, s[12:13]
	global_store_dword v0, v130, s[12:13] offset:128
	v_add_u32_e32 v0, 0x1000, v0
	global_store_dword v0, v131, s[12:13]
	global_store_dword v0, v132, s[12:13] offset:128
	v_add_u32_e32 v0, 0x1000, v0
	global_store_dword v0, v133, s[12:13]
	global_store_dword v0, v134, s[12:13] offset:128
	s_add_i32 s37, s37, s18
	s_add_i32 s36, s36, s19
	s_cmp_lt_i32 s37, s8
	s_cbranch_scc1 .LBB0_79
